# v13 + gate/up (SwiGLU) epilogue re-emitted with packed f32 ops and plain rsq; in-proj epilogue: RoPE math skipped by a wave-uniform branch on non-rotated tiles, denormal-guard around rsq removed (argu
# speedup vs baseline: 1.0131x; 1.0037x over previous
; __device__ __forceinline__ unsigned cvtpk(float lo, float hi) { f32x2 v = {lo, hi}; bf16x2_t b = __builtin_convertvector(v, bf16x2_t); return __builtin_bit_cast(unsigned, b); }
; #define PG8_LAS __attribute__((address_space(3)))
;     __device__ __forceinline__ void operator()(Acc& acc, const Unit& u, int wr, int wc, int fr, int fq, PG8_LAS unsigned char* ldx, const Pre&) const {
;     ...
;         f32x4 g0 = {1.f, 1.f, 1.f, 1.f}, g1 = {1.f, 1.f, 1.f, 1.f};
;         if (normed0) { g0 = *(const f32x4*)(gp + hc); g1 = *(const f32x4*)(gp + hc + 16); }
;         if (isq) { g0 = g0 * C2; g1 = g1 * C2; }
;     ...
;                     f32x4 v0 = acc[ai][bj][m][0], v1 = acc[ai][bj][m][1];
;                     if (normed) {
;                         const f32x2 pr = *(const PG8_LAS f32x2*)(X + (rowl * 2 + bj) * 4 + (wc & 2));
;                         const float rinv = rsqrtf((pr.x + pr.y) * (1.0f / 64.0f) + EPS);
;                         v0 = v0 * rinv * g0; v1 = v1 * rinv * g1;
;                         if (rope) { const f32x4 t0 = v0 * cs - v1 * sn, t1 = v0 * sn + v1 * cs; v0 = t0; v1 = t1; }
;                     }
;                     bf16_t* p = QKV + grow * INC + pn * 256 + bj * 128 + wc * 32 + ((fq & 1) ? 16 + 4 * (fq - 1) : 4 * fq);
;                     u32x2 w0, w1; w0.x = cvtpk(v0[0], v0[1]); w0.y = cvtpk(v0[2], v0[3]); w1.x = cvtpk(v1[0], v1[1]); w1.y = cvtpk(v1[2], v1[3]);
;                     *(u32x4*)p = pair16(w0, w1);
.LBB0_451:
	s_add_i32 s1, s48, -3
	s_cmp_lt_u32 s1, 2
	s_cselect_b64 s[12:13], -1, 0
	s_waitcnt vmcnt(0)
	v_pk_mul_f32 v[210:211], v[164:165], s[26:27] op_sel_hi:[1,0]
	v_pk_mul_f32 v[228:229], v[166:167], s[26:27] op_sel_hi:[1,0]
	s_or_b64 s[2:3], s[2:3], s[12:13]
	v_cndmask_b32_e64 v167, v167, v229, s[2:3]
	v_cndmask_b32_e64 v166, v166, v228, s[2:3]
	v_cndmask_b32_e64 v165, v165, v211, s[2:3]
	v_cndmask_b32_e64 v164, v164, v210, s[2:3]
	v_pk_mul_f32 v[210:211], v[160:161], s[26:27] op_sel_hi:[1,0]
	v_pk_mul_f32 v[228:229], v[162:163], s[26:27] op_sel_hi:[1,0]
	v_cndmask_b32_e64 v161, v161, v211, s[2:3]
	v_cndmask_b32_e64 v163, v163, v229, s[2:3]
	v_cndmask_b32_e64 v162, v162, v228, s[2:3]
	s_and_b64 vcc, exec, s[10:11]
	v_cndmask_b32_e64 v160, v160, v210, s[2:3]
	s_cbranch_vccnz .LBB0_453
	ds_read_b64 v[210:211], v220
	s_waitcnt lgkmcnt(0)
	v_add_f32_e32 v172, v210, v211
	v_fmamk_f32 v172, v172, 0x3c800000, v219
	v_rsq_f32_e32 v172, v172
	s_nop 0
	v_pk_mul_f32 v[146:147], v[146:147], v[172:173] op_sel_hi:[1,0]
	v_pk_mul_f32 v[144:145], v[144:145], v[172:173] op_sel_hi:[1,0]
	v_pk_mul_f32 v[150:151], v[150:151], v[172:173] op_sel_hi:[1,0]
	v_pk_mul_f32 v[148:149], v[148:149], v[172:173] op_sel_hi:[1,0]
	v_pk_mul_f32 v[144:145], v[164:165], v[144:145]
	v_pk_mul_f32 v[146:147], v[166:167], v[146:147]
	v_pk_mul_f32 v[148:149], v[160:161], v[148:149]
	v_pk_mul_f32 v[150:151], v[162:163], v[150:151]
	s_and_b64 vcc, exec, s[8:9]
	s_cbranch_vccz .Lp2_norope_1
	v_pk_mul_f32 v[210:211], v[138:139], v[146:147]
	v_pk_mul_f32 v[228:229], v[136:137], v[144:145]
	v_pk_mul_f32 v[230:231], v[142:143], v[146:147]
	v_pk_mul_f32 v[232:233], v[140:141], v[144:145]
	v_pk_fma_f32 v[228:229], v[140:141], v[148:149], v[228:229] neg_lo:[0,0,1] neg_hi:[0,0,1]
	v_pk_fma_f32 v[210:211], v[142:143], v[150:151], v[210:211] neg_lo:[0,0,1] neg_hi:[0,0,1]
	v_pk_fma_f32 v[232:233], v[136:137], v[148:149], v[232:233]
	v_pk_fma_f32 v[230:231], v[138:139], v[150:151], v[230:231]
	v_cndmask_b32_e64 v151, v151, v211, s[8:9]
	v_cndmask_b32_e64 v150, v150, v210, s[8:9]
	v_cndmask_b32_e64 v149, v149, v229, s[8:9]
	v_cndmask_b32_e64 v148, v148, v228, s[8:9]
	v_cndmask_b32_e64 v147, v147, v231, s[8:9]
	v_cndmask_b32_e64 v146, v146, v230, s[8:9]
	v_cndmask_b32_e64 v145, v145, v233, s[8:9]
	v_cndmask_b32_e64 v144, v144, v232, s[8:9]
.Lp2_norope_1:
.LBB0_453:
	s_ashr_i32 s47, s46, 31
	s_lshl_b32 s2, s48, 8
	s_lshl_b64 s[48:49], s[46:47], 8
	v_lshl_add_u64 v[210:211], s[48:49], 0, v[174:175]
	v_mov_b64_e32 v[228:229], s[24:25]
	v_mad_u64_u32 v[228:229], s[12:13], v210, s79, v[228:229]
	s_ashr_i32 s3, s2, 31
	v_mad_i32_i24 v229, v211, s79, v229
	v_lshl_add_u64 v[210:211], s[2:3], 1, v[228:229]
	v_lshl_add_u64 v[210:211], v[210:211], 0, s[36:37]
	v_cvt_pk_bf16_f32 v148, v148, v149
	v_cvt_pk_bf16_f32 v149, v150, v151
	v_cvt_pk_bf16_f32 v150, v144, v145
	v_cvt_pk_bf16_f32 v151, v146, v147
	v_cndmask_b32_e64 v144, 0, 1, s[50:51]
	v_lshl_add_u64 v[210:211], v[176:177], 1, v[210:211]
	v_permlane16_swap_b32_e32 v148, v150
	v_permlane16_swap_b32_e32 v149, v151
	v_cmp_ne_u32_e64 s[12:13], 1, v144
	s_andn2_b64 vcc, exec, s[50:51]
	global_store_dwordx4 v[210:211], v[148:151], off
	s_cbranch_vccnz .LBB0_455
	ds_read_b64 v[144:145], v220 offset:16
	s_waitcnt lgkmcnt(0)
	v_add_f32_e32 v144, v144, v145
	v_fmamk_f32 v144, v144, 0x3c800000, v219
	v_rsq_f32_e32 v144, v144
	s_nop 0
	v_pk_mul_f32 v[130:131], v[130:131], v[144:145] op_sel_hi:[1,0]
	v_pk_mul_f32 v[128:129], v[128:129], v[144:145] op_sel_hi:[1,0]
	v_pk_mul_f32 v[134:135], v[134:135], v[144:145] op_sel_hi:[1,0]
	v_pk_mul_f32 v[132:133], v[132:133], v[144:145] op_sel_hi:[1,0]
	v_pk_mul_f32 v[128:129], v[164:165], v[128:129]
	v_pk_mul_f32 v[130:131], v[166:167], v[130:131]
	v_pk_mul_f32 v[132:133], v[160:161], v[132:133]
	v_pk_mul_f32 v[134:135], v[162:163], v[134:135]
	s_and_b64 vcc, exec, s[8:9]
	s_cbranch_vccz .Lp2_norope_2
	v_pk_mul_f32 v[144:145], v[138:139], v[130:131]
	v_pk_mul_f32 v[146:147], v[136:137], v[128:129]
	v_pk_mul_f32 v[148:149], v[142:143], v[130:131]
	v_pk_mul_f32 v[150:151], v[140:141], v[128:129]
	v_pk_fma_f32 v[146:147], v[140:141], v[132:133], v[146:147] neg_lo:[0,0,1] neg_hi:[0,0,1]
	v_pk_fma_f32 v[144:145], v[142:143], v[134:135], v[144:145] neg_lo:[0,0,1] neg_hi:[0,0,1]
	v_pk_fma_f32 v[150:151], v[136:137], v[132:133], v[150:151]
	v_pk_fma_f32 v[148:149], v[138:139], v[134:135], v[148:149]
	v_cndmask_b32_e64 v135, v135, v145, s[8:9]
	v_cndmask_b32_e64 v134, v134, v144, s[8:9]
	v_cndmask_b32_e64 v133, v133, v147, s[8:9]
	v_cndmask_b32_e64 v132, v132, v146, s[8:9]
	v_cndmask_b32_e64 v131, v131, v149, s[8:9]
	v_cndmask_b32_e64 v130, v130, v148, s[8:9]
	v_cndmask_b32_e64 v129, v129, v151, s[8:9]
	v_cndmask_b32_e64 v128, v128, v150, s[8:9]
; __device__ __forceinline__ unsigned cvtpk(float lo, float hi) { f32x2 v = {lo, hi}; bf16x2_t b = __builtin_convertvector(v, bf16x2_t); return __builtin_bit_cast(unsigned, b); }
; #define PG8_LAS __attribute__((address_space(3)))
;     __device__ __forceinline__ void operator()(Acc& acc, const Unit& u, int wr, int wc, int fr, int fq, PG8_LAS unsigned char* ldx, const Pre&) const {
;     ...
;             for (int m = 0; m < 4; ++m) {
;                 const int rowl = ai * 128 + wr * 64 + m * 16 + fr;
;                 const size_t grow = (size_t)u.pm * 256 + rowl;
;                 const f32x4 cs = rc[m], sn = rs[m];
; #pragma unroll
;                 for (int bj = 0; bj < 2; ++bj) {
;                     const bool normed = bj == 0 ? normed0 : normed1;
;                     f32x4 v0 = acc[ai][bj][m][0], v1 = acc[ai][bj][m][1];
;                     if (normed) {
;                         const f32x2 pr = *(const PG8_LAS f32x2*)(X + (rowl * 2 + bj) * 4 + (wc & 2));
;                         const float rinv = rsqrtf((pr.x + pr.y) * (1.0f / 64.0f) + EPS);
;                         v0 = v0 * rinv * g0; v1 = v1 * rinv * g1;
;                         if (rope) { const f32x4 t0 = v0 * cs - v1 * sn, t1 = v0 * sn + v1 * cs; v0 = t0; v1 = t1; }
;                     }
;                     bf16_t* p = QKV + grow * INC + pn * 256 + bj * 128 + wc * 32 + ((fq & 1) ? 16 + 4 * (fq - 1) : 4 * fq);
;                     u32x2 w0, w1; w0.x = cvtpk(v0[0], v0[1]); w0.y = cvtpk(v0[2], v0[3]); w1.x = cvtpk(v1[0], v1[1]); w1.y = cvtpk(v1[2], v1[3]);
;                     *(u32x4*)p = pair16(w0, w1);
.Lp2_norope_2:
.LBB0_455:
	v_cvt_pk_bf16_f32 v132, v132, v133
	v_cvt_pk_bf16_f32 v133, v134, v135
	v_cvt_pk_bf16_f32 v134, v128, v129
	v_cvt_pk_bf16_f32 v135, v130, v131
	s_nop 0
	v_permlane16_swap_b32_e32 v132, v134
	v_permlane16_swap_b32_e32 v133, v135
	global_store_dwordx4 v[210:211], v[132:135], off offset:256
	s_and_b64 vcc, exec, s[10:11]
	s_cbranch_vccnz .LBB0_457
	ds_read_b64 v[128:129], v221
	s_waitcnt lgkmcnt(0)
	v_add_f32_e32 v128, v128, v129
	v_fmamk_f32 v128, v128, 0x3c800000, v219
	v_rsq_f32_e32 v128, v128
	s_nop 0
	v_pk_mul_f32 v[122:123], v[122:123], v[128:129] op_sel_hi:[1,0]
	v_pk_mul_f32 v[120:121], v[120:121], v[128:129] op_sel_hi:[1,0]
	v_pk_mul_f32 v[126:127], v[126:127], v[128:129] op_sel_hi:[1,0]
	v_pk_mul_f32 v[124:125], v[124:125], v[128:129] op_sel_hi:[1,0]
	v_pk_mul_f32 v[120:121], v[164:165], v[120:121]
	v_pk_mul_f32 v[122:123], v[166:167], v[122:123]
	v_pk_mul_f32 v[124:125], v[160:161], v[124:125]
	v_pk_mul_f32 v[126:127], v[162:163], v[126:127]
	s_and_b64 vcc, exec, s[8:9]
	s_cbranch_vccz .Lp2_norope_3
	v_pk_mul_f32 v[128:129], v[114:115], v[122:123]
	v_pk_mul_f32 v[130:131], v[112:113], v[120:121]
	v_pk_mul_f32 v[132:133], v[118:119], v[122:123]
	v_pk_mul_f32 v[134:135], v[116:117], v[120:121]
	v_pk_fma_f32 v[130:131], v[116:117], v[124:125], v[130:131] neg_lo:[0,0,1] neg_hi:[0,0,1]
	v_pk_fma_f32 v[128:129], v[118:119], v[126:127], v[128:129] neg_lo:[0,0,1] neg_hi:[0,0,1]
	v_pk_fma_f32 v[134:135], v[112:113], v[124:125], v[134:135]
	v_pk_fma_f32 v[132:133], v[114:115], v[126:127], v[132:133]
	v_cndmask_b32_e64 v127, v127, v129, s[8:9]
	v_cndmask_b32_e64 v126, v126, v128, s[8:9]
	v_cndmask_b32_e64 v125, v125, v131, s[8:9]
	v_cndmask_b32_e64 v124, v124, v130, s[8:9]
	v_cndmask_b32_e64 v123, v123, v133, s[8:9]
	v_cndmask_b32_e64 v122, v122, v132, s[8:9]
	v_cndmask_b32_e64 v121, v121, v135, s[8:9]
	v_cndmask_b32_e64 v120, v120, v134, s[8:9]
.Lp2_norope_3:
.LBB0_457:
	v_lshl_add_u64 v[128:129], s[48:49], 0, v[178:179]
	v_mov_b64_e32 v[130:131], s[24:25]
	v_mad_u64_u32 v[130:131], s[50:51], v128, s79, v[130:131]
	v_mad_i32_i24 v131, v129, s79, v131
	v_lshl_add_u64 v[128:129], s[2:3], 1, v[130:131]
	v_lshl_add_u64 v[128:129], v[128:129], 0, s[36:37]
	v_cvt_pk_bf16_f32 v124, v124, v125
	v_cvt_pk_bf16_f32 v125, v126, v127
	v_cvt_pk_bf16_f32 v126, v120, v121
	v_cvt_pk_bf16_f32 v127, v122, v123
	v_lshl_add_u64 v[128:129], v[176:177], 1, v[128:129]
	v_permlane16_swap_b32_e32 v124, v126
	v_permlane16_swap_b32_e32 v125, v127
	s_and_b64 vcc, exec, s[12:13]
	global_store_dwordx4 v[128:129], v[124:127], off
	s_cbranch_vccnz .LBB0_459
	ds_read_b64 v[120:121], v221 offset:16
	s_waitcnt lgkmcnt(0)
	v_add_f32_e32 v120, v120, v121
	v_fmamk_f32 v120, v120, 0x3c800000, v219
	v_rsq_f32_e32 v120, v120
	s_nop 0
	v_pk_mul_f32 v[106:107], v[106:107], v[120:121] op_sel_hi:[1,0]
	v_pk_mul_f32 v[104:105], v[104:105], v[120:121] op_sel_hi:[1,0]
	v_pk_mul_f32 v[110:111], v[110:111], v[120:121] op_sel_hi:[1,0]
	v_pk_mul_f32 v[108:109], v[108:109], v[120:121] op_sel_hi:[1,0]
	v_pk_mul_f32 v[104:105], v[164:165], v[104:105]
	v_pk_mul_f32 v[106:107], v[166:167], v[106:107]
	v_pk_mul_f32 v[108:109], v[160:161], v[108:109]
	v_pk_mul_f32 v[110:111], v[162:163], v[110:111]
	s_and_b64 vcc, exec, s[8:9]
	s_cbranch_vccz .Lp2_norope_4
	v_pk_mul_f32 v[120:121], v[114:115], v[106:107]
	v_pk_mul_f32 v[122:123], v[112:113], v[104:105]
	v_pk_mul_f32 v[124:125], v[118:119], v[106:107]
	v_pk_mul_f32 v[126:127], v[116:117], v[104:105]
	v_pk_fma_f32 v[122:123], v[116:117], v[108:109], v[122:123] neg_lo:[0,0,1] neg_hi:[0,0,1]
	v_pk_fma_f32 v[120:121], v[118:119], v[110:111], v[120:121] neg_lo:[0,0,1] neg_hi:[0,0,1]
	v_pk_fma_f32 v[126:127], v[112:113], v[108:109], v[126:127]
	v_pk_fma_f32 v[124:125], v[114:115], v[110:111], v[124:125]
	v_cndmask_b32_e64 v111, v111, v121, s[8:9]
	v_cndmask_b32_e64 v110, v110, v120, s[8:9]
	v_cndmask_b32_e64 v109, v109, v123, s[8:9]
	v_cndmask_b32_e64 v108, v108, v122, s[8:9]
	v_cndmask_b32_e64 v107, v107, v125, s[8:9]
	v_cndmask_b32_e64 v106, v106, v124, s[8:9]
	v_cndmask_b32_e64 v105, v105, v127, s[8:9]
	v_cndmask_b32_e64 v104, v104, v126, s[8:9]
.Lp2_norope_4:
.LBB0_459:
	v_cvt_pk_bf16_f32 v108, v108, v109
	v_cvt_pk_bf16_f32 v109, v110, v111
	v_cvt_pk_bf16_f32 v110, v104, v105
	v_cvt_pk_bf16_f32 v111, v106, v107
	s_nop 0
	v_permlane16_swap_b32_e32 v108, v110
	v_permlane16_swap_b32_e32 v109, v111
	global_store_dwordx4 v[128:129], v[108:111], off offset:256
	s_and_b64 vcc, exec, s[10:11]
	s_cbranch_vccnz .LBB0_461
	ds_read_b64 v[104:105], v222
	s_waitcnt lgkmcnt(0)
	v_add_f32_e32 v104, v104, v105
	v_fmamk_f32 v104, v104, 0x3c800000, v219
	v_rsq_f32_e32 v104, v104
	s_nop 0
	v_pk_mul_f32 v[98:99], v[98:99], v[104:105] op_sel_hi:[1,0]
	v_pk_mul_f32 v[96:97], v[96:97], v[104:105] op_sel_hi:[1,0]
	v_pk_mul_f32 v[102:103], v[102:103], v[104:105] op_sel_hi:[1,0]
	v_pk_mul_f32 v[100:101], v[100:101], v[104:105] op_sel_hi:[1,0]
	v_pk_mul_f32 v[96:97], v[164:165], v[96:97]
	v_pk_mul_f32 v[98:99], v[166:167], v[98:99]
	v_pk_mul_f32 v[100:101], v[160:161], v[100:101]
	v_pk_mul_f32 v[102:103], v[162:163], v[102:103]
	s_and_b64 vcc, exec, s[8:9]
	s_cbranch_vccz .Lp2_norope_5
	v_pk_mul_f32 v[104:105], v[90:91], v[98:99]
	v_pk_mul_f32 v[106:107], v[88:89], v[96:97]
	v_pk_mul_f32 v[108:109], v[94:95], v[98:99]
	v_pk_mul_f32 v[110:111], v[92:93], v[96:97]
	v_pk_fma_f32 v[106:107], v[92:93], v[100:101], v[106:107] neg_lo:[0,0,1] neg_hi:[0,0,1]
	v_pk_fma_f32 v[104:105], v[94:95], v[102:103], v[104:105] neg_lo:[0,0,1] neg_hi:[0,0,1]
	v_pk_fma_f32 v[110:111], v[88:89], v[100:101], v[110:111]
	v_pk_fma_f32 v[108:109], v[90:91], v[102:103], v[108:109]
	v_cndmask_b32_e64 v103, v103, v105, s[8:9]
	v_cndmask_b32_e64 v102, v102, v104, s[8:9]
	v_cndmask_b32_e64 v101, v101, v107, s[8:9]
	v_cndmask_b32_e64 v100, v100, v106, s[8:9]
	v_cndmask_b32_e64 v99, v99, v109, s[8:9]
	v_cndmask_b32_e64 v98, v98, v108, s[8:9]
	v_cndmask_b32_e64 v97, v97, v111, s[8:9]
	v_cndmask_b32_e64 v96, v96, v110, s[8:9]
; __device__ __forceinline__ unsigned cvtpk(float lo, float hi) { f32x2 v = {lo, hi}; bf16x2_t b = __builtin_convertvector(v, bf16x2_t); return __builtin_bit_cast(unsigned, b); }
; #define PG8_LAS __attribute__((address_space(3)))
;     __device__ __forceinline__ void operator()(Acc& acc, const Unit& u, int wr, int wc, int fr, int fq, PG8_LAS unsigned char* ldx, const Pre&) const {
;     ...
;             for (int m = 0; m < 4; ++m) {
;                 const int rowl = ai * 128 + wr * 64 + m * 16 + fr;
;                 const size_t grow = (size_t)u.pm * 256 + rowl;
;                 const f32x4 cs = rc[m], sn = rs[m];
; #pragma unroll
;                 for (int bj = 0; bj < 2; ++bj) {
;                     const bool normed = bj == 0 ? normed0 : normed1;
;                     f32x4 v0 = acc[ai][bj][m][0], v1 = acc[ai][bj][m][1];
;                     if (normed) {
;                         const f32x2 pr = *(const PG8_LAS f32x2*)(X + (rowl * 2 + bj) * 4 + (wc & 2));
;                         const float rinv = rsqrtf((pr.x + pr.y) * (1.0f / 64.0f) + EPS);
;                         v0 = v0 * rinv * g0; v1 = v1 * rinv * g1;
;                         if (rope) { const f32x4 t0 = v0 * cs - v1 * sn, t1 = v0 * sn + v1 * cs; v0 = t0; v1 = t1; }
;                     }
;                     bf16_t* p = QKV + grow * INC + pn * 256 + bj * 128 + wc * 32 + ((fq & 1) ? 16 + 4 * (fq - 1) : 4 * fq);
;                     u32x2 w0, w1; w0.x = cvtpk(v0[0], v0[1]); w0.y = cvtpk(v0[2], v0[3]); w1.x = cvtpk(v1[0], v1[1]); w1.y = cvtpk(v1[2], v1[3]);
;                     *(u32x4*)p = pair16(w0, w1);
.Lp2_norope_5:
.LBB0_461:
	v_lshl_add_u64 v[104:105], s[48:49], 0, v[180:181]
	v_mov_b64_e32 v[106:107], s[24:25]
	v_mad_u64_u32 v[106:107], s[50:51], v104, s79, v[106:107]
	v_mad_i32_i24 v107, v105, s79, v107
	v_lshl_add_u64 v[104:105], s[2:3], 1, v[106:107]
	v_lshl_add_u64 v[104:105], v[104:105], 0, s[36:37]
	v_cvt_pk_bf16_f32 v100, v100, v101
	v_cvt_pk_bf16_f32 v101, v102, v103
	v_cvt_pk_bf16_f32 v102, v96, v97
	v_cvt_pk_bf16_f32 v103, v98, v99
	v_lshl_add_u64 v[104:105], v[176:177], 1, v[104:105]
	v_permlane16_swap_b32_e32 v100, v102
	v_permlane16_swap_b32_e32 v101, v103
	s_and_b64 vcc, exec, s[12:13]
	global_store_dwordx4 v[104:105], v[100:103], off
	s_cbranch_vccnz .LBB0_463
	ds_read_b64 v[96:97], v222 offset:16
	s_waitcnt lgkmcnt(0)
	v_add_f32_e32 v96, v96, v97
	v_fmamk_f32 v96, v96, 0x3c800000, v219
	v_rsq_f32_e32 v96, v96
	s_nop 0
	v_pk_mul_f32 v[82:83], v[82:83], v[96:97] op_sel_hi:[1,0]
	v_pk_mul_f32 v[80:81], v[80:81], v[96:97] op_sel_hi:[1,0]
	v_pk_mul_f32 v[86:87], v[86:87], v[96:97] op_sel_hi:[1,0]
	v_pk_mul_f32 v[84:85], v[84:85], v[96:97] op_sel_hi:[1,0]
	v_pk_mul_f32 v[80:81], v[164:165], v[80:81]
	v_pk_mul_f32 v[82:83], v[166:167], v[82:83]
	v_pk_mul_f32 v[84:85], v[160:161], v[84:85]
	v_pk_mul_f32 v[86:87], v[162:163], v[86:87]
	s_and_b64 vcc, exec, s[8:9]
	s_cbranch_vccz .Lp2_norope_6
	v_pk_mul_f32 v[96:97], v[90:91], v[82:83]
	v_pk_mul_f32 v[98:99], v[88:89], v[80:81]
	v_pk_mul_f32 v[100:101], v[94:95], v[82:83]
	v_pk_mul_f32 v[102:103], v[92:93], v[80:81]
	v_pk_fma_f32 v[98:99], v[92:93], v[84:85], v[98:99] neg_lo:[0,0,1] neg_hi:[0,0,1]
	v_pk_fma_f32 v[96:97], v[94:95], v[86:87], v[96:97] neg_lo:[0,0,1] neg_hi:[0,0,1]
	v_pk_fma_f32 v[102:103], v[88:89], v[84:85], v[102:103]
	v_pk_fma_f32 v[100:101], v[90:91], v[86:87], v[100:101]
	v_cndmask_b32_e64 v87, v87, v97, s[8:9]
	v_cndmask_b32_e64 v86, v86, v96, s[8:9]
	v_cndmask_b32_e64 v85, v85, v99, s[8:9]
	v_cndmask_b32_e64 v84, v84, v98, s[8:9]
	v_cndmask_b32_e64 v83, v83, v101, s[8:9]
	v_cndmask_b32_e64 v82, v82, v100, s[8:9]
	v_cndmask_b32_e64 v81, v81, v103, s[8:9]
	v_cndmask_b32_e64 v80, v80, v102, s[8:9]
.Lp2_norope_6:
.LBB0_463:
	v_cvt_pk_bf16_f32 v84, v84, v85
	v_cvt_pk_bf16_f32 v85, v86, v87
	v_cvt_pk_bf16_f32 v86, v80, v81
	v_cvt_pk_bf16_f32 v87, v82, v83
	s_nop 0
	v_permlane16_swap_b32_e32 v84, v86
	v_permlane16_swap_b32_e32 v85, v87
	global_store_dwordx4 v[104:105], v[84:87], off offset:256
	s_and_b64 vcc, exec, s[10:11]
	s_cbranch_vccnz .LBB0_465
	ds_read_b64 v[80:81], v223
	s_waitcnt lgkmcnt(0)
	v_add_f32_e32 v80, v80, v81
	v_fmamk_f32 v80, v80, 0x3c800000, v219
	v_rsq_f32_e32 v80, v80
	s_nop 0
	v_pk_mul_f32 v[74:75], v[74:75], v[80:81] op_sel_hi:[1,0]
	v_pk_mul_f32 v[72:73], v[72:73], v[80:81] op_sel_hi:[1,0]
	v_pk_mul_f32 v[78:79], v[78:79], v[80:81] op_sel_hi:[1,0]
	v_pk_mul_f32 v[76:77], v[76:77], v[80:81] op_sel_hi:[1,0]
	v_pk_mul_f32 v[72:73], v[164:165], v[72:73]
	v_pk_mul_f32 v[74:75], v[166:167], v[74:75]
	v_pk_mul_f32 v[76:77], v[160:161], v[76:77]
	v_pk_mul_f32 v[78:79], v[162:163], v[78:79]
	s_and_b64 vcc, exec, s[8:9]
	s_cbranch_vccz .Lp2_norope_7
	v_pk_mul_f32 v[80:81], v[158:159], v[74:75]
	v_pk_mul_f32 v[82:83], v[156:157], v[72:73]
	v_pk_mul_f32 v[84:85], v[154:155], v[74:75]
	v_pk_mul_f32 v[86:87], v[152:153], v[72:73]
	v_pk_fma_f32 v[82:83], v[152:153], v[76:77], v[82:83] neg_lo:[0,0,1] neg_hi:[0,0,1]
	v_pk_fma_f32 v[80:81], v[154:155], v[78:79], v[80:81] neg_lo:[0,0,1] neg_hi:[0,0,1]
	v_pk_fma_f32 v[86:87], v[156:157], v[76:77], v[86:87]
	v_pk_fma_f32 v[84:85], v[158:159], v[78:79], v[84:85]
	v_cndmask_b32_e64 v79, v79, v81, s[8:9]
	v_cndmask_b32_e64 v78, v78, v80, s[8:9]
	v_cndmask_b32_e64 v77, v77, v83, s[8:9]
	v_cndmask_b32_e64 v76, v76, v82, s[8:9]
	v_cndmask_b32_e64 v75, v75, v85, s[8:9]
	v_cndmask_b32_e64 v74, v74, v84, s[8:9]
	v_cndmask_b32_e64 v73, v73, v87, s[8:9]
	v_cndmask_b32_e64 v72, v72, v86, s[8:9]
.Lp2_norope_7:
.LBB0_465:
	v_lshl_add_u64 v[80:81], s[48:49], 0, v[182:183]
	v_mov_b64_e32 v[82:83], s[24:25]
	v_mad_u64_u32 v[82:83], s[50:51], v80, s79, v[82:83]
	v_mad_i32_i24 v83, v81, s79, v83
	v_lshl_add_u64 v[80:81], s[2:3], 1, v[82:83]
	v_lshl_add_u64 v[80:81], v[80:81], 0, s[36:37]
	v_cvt_pk_bf16_f32 v76, v76, v77
	v_cvt_pk_bf16_f32 v77, v78, v79
	v_cvt_pk_bf16_f32 v78, v72, v73
	v_cvt_pk_bf16_f32 v79, v74, v75
	v_lshl_add_u64 v[80:81], v[176:177], 1, v[80:81]
	v_permlane16_swap_b32_e32 v76, v78
	v_permlane16_swap_b32_e32 v77, v79
	s_and_b64 vcc, exec, s[12:13]
	global_store_dwordx4 v[80:81], v[76:79], off
	s_cbranch_vccnz .LBB0_467
	ds_read_b64 v[72:73], v223 offset:16
	s_waitcnt lgkmcnt(0)
	v_add_f32_e32 v72, v72, v73
	v_fmamk_f32 v72, v72, 0x3c800000, v219
	v_rsq_f32_e32 v72, v72
	s_nop 0
	v_pk_mul_f32 v[66:67], v[66:67], v[72:73] op_sel_hi:[1,0]
	v_pk_mul_f32 v[64:65], v[64:65], v[72:73] op_sel_hi:[1,0]
	v_pk_mul_f32 v[70:71], v[70:71], v[72:73] op_sel_hi:[1,0]
	v_pk_mul_f32 v[68:69], v[68:69], v[72:73] op_sel_hi:[1,0]
	v_pk_mul_f32 v[64:65], v[164:165], v[64:65]
	v_pk_mul_f32 v[66:67], v[166:167], v[66:67]
	v_pk_mul_f32 v[68:69], v[160:161], v[68:69]
	v_pk_mul_f32 v[70:71], v[162:163], v[70:71]
	s_and_b64 vcc, exec, s[8:9]
	s_cbranch_vccz .Lp2_norope_8
	v_pk_mul_f32 v[72:73], v[158:159], v[66:67]
	v_pk_mul_f32 v[74:75], v[156:157], v[64:65]
	v_pk_mul_f32 v[76:77], v[154:155], v[66:67]
	v_pk_mul_f32 v[78:79], v[152:153], v[64:65]
	v_pk_fma_f32 v[74:75], v[152:153], v[68:69], v[74:75] neg_lo:[0,0,1] neg_hi:[0,0,1]
	v_pk_fma_f32 v[72:73], v[154:155], v[70:71], v[72:73] neg_lo:[0,0,1] neg_hi:[0,0,1]
	v_pk_fma_f32 v[78:79], v[156:157], v[68:69], v[78:79]
	v_pk_fma_f32 v[76:77], v[158:159], v[70:71], v[76:77]
	v_cndmask_b32_e64 v71, v71, v73, s[8:9]
	v_cndmask_b32_e64 v70, v70, v72, s[8:9]
	v_cndmask_b32_e64 v69, v69, v75, s[8:9]
	v_cndmask_b32_e64 v68, v68, v74, s[8:9]
	v_cndmask_b32_e64 v67, v67, v77, s[8:9]
	v_cndmask_b32_e64 v66, v66, v76, s[8:9]
	v_cndmask_b32_e64 v65, v65, v79, s[8:9]
	v_cndmask_b32_e64 v64, v64, v78, s[8:9]
; __device__ __forceinline__ unsigned cvtpk(float lo, float hi) { f32x2 v = {lo, hi}; bf16x2_t b = __builtin_convertvector(v, bf16x2_t); return __builtin_bit_cast(unsigned, b); }
; #define PG8_LAS __attribute__((address_space(3)))
;     __device__ __forceinline__ void operator()(Acc& acc, const Unit& u, int wr, int wc, int fr, int fq, PG8_LAS unsigned char* ldx, const Pre&) const {
;     ...
;             if (ai == 1 && rope && !(wc & 1)) {
; #pragma unroll
;                 for (int m = 0; m < 4; ++m) { const int pos = (4 * u.pm + 2 + wr) & 63; rc[m] = *(const f32x4*)(ropec + pos * 16 + 4 * fq); rs[m] = *(const f32x4*)(ropes + pos * 16 + 4 * fq); }
;             }
; #pragma unroll
;             for (int m = 0; m < 4; ++m) {
;                 const int rowl = ai * 128 + wr * 64 + m * 16 + fr;
;                 const size_t grow = (size_t)u.pm * 256 + rowl;
;                 const f32x4 cs = rc[m], sn = rs[m];
; #pragma unroll
;                 for (int bj = 0; bj < 2; ++bj) {
;                     const bool normed = bj == 0 ? normed0 : normed1;
;                     f32x4 v0 = acc[ai][bj][m][0], v1 = acc[ai][bj][m][1];
;                     if (normed) {
;                         const f32x2 pr = *(const PG8_LAS f32x2*)(X + (rowl * 2 + bj) * 4 + (wc & 2));
;                         const float rinv = rsqrtf((pr.x + pr.y) * (1.0f / 64.0f) + EPS);
;                         v0 = v0 * rinv * g0; v1 = v1 * rinv * g1;
;                         if (rope) { const f32x4 t0 = v0 * cs - v1 * sn, t1 = v0 * sn + v1 * cs; v0 = t0; v1 = t1; }
;                     }
;                     bf16_t* p = QKV + grow * INC + pn * 256 + bj * 128 + wc * 32 + ((fq & 1) ? 16 + 4 * (fq - 1) : 4 * fq);
;                     u32x2 w0, w1; w0.x = cvtpk(v0[0], v0[1]); w0.y = cvtpk(v0[2], v0[3]); w1.x = cvtpk(v1[0], v1[1]); w1.y = cvtpk(v1[2], v1[3]);
;                     *(u32x4*)p = pair16(w0, w1);
.Lp2_norope_8:
.LBB0_467:
	v_cvt_pk_bf16_f32 v68, v68, v69
	v_cvt_pk_bf16_f32 v69, v70, v71
	v_cvt_pk_bf16_f32 v70, v64, v65
	v_cvt_pk_bf16_f32 v71, v66, v67
	s_nop 0
	v_permlane16_swap_b32_e32 v68, v70
	v_permlane16_swap_b32_e32 v69, v71
	global_store_dwordx4 v[80:81], v[68:71], off offset:256
	s_and_b64 s[50:51], s[16:17], s[8:9]
	s_andn2_b64 vcc, exec, s[50:51]
	s_cbranch_vccnz .LBB0_469
	s_lshl_b32 s1, s46, 6
	s_add_i32 s1, s65, s1
	s_and_b32 s1, s1, 0x3f0
	s_lshl_b32 s46, s1, 2
	s_mov_b32 s47, s37
	v_lshl_add_u64 v[64:65], v[196:197], 0, s[46:47]
	global_load_dwordx4 v[116:119], v[64:65], off
	v_lshl_add_u64 v[64:65], v[194:195], 0, s[46:47]
	global_load_dwordx4 v[112:115], v[64:65], off
	s_waitcnt vmcnt(1)
	v_mov_b32_e32 v92, v116
	v_mov_b32_e32 v93, v117
	v_mov_b32_e32 v94, v118
	v_mov_b32_e32 v95, v119
	v_mov_b32_e32 v206, v116
	v_mov_b32_e32 v207, v117
	v_mov_b32_e32 v208, v118
	v_mov_b32_e32 v209, v119
	s_waitcnt vmcnt(0)
	v_mov_b32_e32 v88, v112
	v_mov_b32_e32 v89, v113
	v_mov_b32_e32 v90, v114
	v_mov_b32_e32 v91, v115
	v_mov_b32_e32 v202, v112
	v_mov_b32_e32 v203, v113
	v_mov_b32_e32 v204, v114
	v_mov_b32_e32 v205, v115
	v_mov_b32_e32 v136, v112
	v_mov_b32_e32 v137, v113
	v_mov_b32_e32 v138, v114
	v_mov_b32_e32 v139, v115
	v_mov_b32_e32 v140, v116
	v_mov_b32_e32 v141, v117
	v_mov_b32_e32 v142, v118
	v_mov_b32_e32 v143, v119
.LBB0_469:
	s_and_b64 vcc, exec, s[10:11]
	s_cbranch_vccnz .LBB0_471
	ds_read_b64 v[64:65], v224
	s_waitcnt lgkmcnt(0)
	v_add_f32_e32 v64, v64, v65
	v_fmamk_f32 v64, v64, 0x3c800000, v219
	v_rsq_f32_e32 v64, v64
	s_nop 0
	v_pk_mul_f32 v[58:59], v[58:59], v[64:65] op_sel_hi:[1,0]
	v_pk_mul_f32 v[56:57], v[56:57], v[64:65] op_sel_hi:[1,0]
	v_pk_mul_f32 v[62:63], v[62:63], v[64:65] op_sel_hi:[1,0]
	v_pk_mul_f32 v[60:61], v[60:61], v[64:65] op_sel_hi:[1,0]
	v_pk_mul_f32 v[56:57], v[164:165], v[56:57]
	v_pk_mul_f32 v[58:59], v[166:167], v[58:59]
	v_pk_mul_f32 v[60:61], v[160:161], v[60:61]
	v_pk_mul_f32 v[62:63], v[162:163], v[62:63]
	s_and_b64 vcc, exec, s[8:9]
	s_cbranch_vccz .Lp2_norope_9
	v_pk_mul_f32 v[64:65], v[138:139], v[58:59]
	v_pk_mul_f32 v[66:67], v[136:137], v[56:57]
	v_pk_mul_f32 v[68:69], v[142:143], v[58:59]
	v_pk_mul_f32 v[70:71], v[140:141], v[56:57]
	v_pk_fma_f32 v[66:67], v[140:141], v[60:61], v[66:67] neg_lo:[0,0,1] neg_hi:[0,0,1]
	v_pk_fma_f32 v[64:65], v[142:143], v[62:63], v[64:65] neg_lo:[0,0,1] neg_hi:[0,0,1]
	v_pk_fma_f32 v[70:71], v[136:137], v[60:61], v[70:71]
	v_pk_fma_f32 v[68:69], v[138:139], v[62:63], v[68:69]
	v_cndmask_b32_e64 v63, v63, v65, s[8:9]
	v_cndmask_b32_e64 v62, v62, v64, s[8:9]
	v_cndmask_b32_e64 v61, v61, v67, s[8:9]
	v_cndmask_b32_e64 v60, v60, v66, s[8:9]
	v_cndmask_b32_e64 v59, v59, v69, s[8:9]
	v_cndmask_b32_e64 v58, v58, v68, s[8:9]
	v_cndmask_b32_e64 v57, v57, v71, s[8:9]
	v_cndmask_b32_e64 v56, v56, v70, s[8:9]
.Lp2_norope_9:
.LBB0_471:
	v_lshl_add_u64 v[64:65], s[48:49], 0, v[184:185]
	v_mov_b64_e32 v[66:67], s[24:25]
	v_mad_u64_u32 v[66:67], s[46:47], v64, s79, v[66:67]
	v_mad_i32_i24 v67, v65, s79, v67
	v_lshl_add_u64 v[64:65], s[2:3], 1, v[66:67]
	v_lshl_add_u64 v[64:65], v[64:65], 0, s[36:37]
	v_cvt_pk_bf16_f32 v60, v60, v61
	v_cvt_pk_bf16_f32 v61, v62, v63
	v_cvt_pk_bf16_f32 v62, v56, v57
	v_cvt_pk_bf16_f32 v63, v58, v59
	v_lshl_add_u64 v[64:65], v[176:177], 1, v[64:65]
	v_permlane16_swap_b32_e32 v60, v62
	v_permlane16_swap_b32_e32 v61, v63
	s_and_b64 vcc, exec, s[12:13]
	global_store_dwordx4 v[64:65], v[60:63], off
	s_cbranch_vccnz .LBB0_473
	ds_read_b64 v[56:57], v224 offset:16
	s_waitcnt lgkmcnt(0)
	v_add_f32_e32 v56, v56, v57
	v_fmamk_f32 v56, v56, 0x3c800000, v219
	v_rsq_f32_e32 v56, v56
	s_nop 0
	v_pk_mul_f32 v[50:51], v[50:51], v[56:57] op_sel_hi:[1,0]
	v_pk_mul_f32 v[48:49], v[48:49], v[56:57] op_sel_hi:[1,0]
	v_pk_mul_f32 v[54:55], v[54:55], v[56:57] op_sel_hi:[1,0]
	v_pk_mul_f32 v[52:53], v[52:53], v[56:57] op_sel_hi:[1,0]
	v_pk_mul_f32 v[48:49], v[164:165], v[48:49]
	v_pk_mul_f32 v[50:51], v[166:167], v[50:51]
	v_pk_mul_f32 v[52:53], v[160:161], v[52:53]
	v_pk_mul_f32 v[54:55], v[162:163], v[54:55]
	s_and_b64 vcc, exec, s[8:9]
	s_cbranch_vccz .Lp2_norope_10
	v_pk_mul_f32 v[56:57], v[138:139], v[50:51]
	v_pk_mul_f32 v[58:59], v[136:137], v[48:49]
	v_pk_mul_f32 v[60:61], v[142:143], v[50:51]
	v_pk_mul_f32 v[62:63], v[140:141], v[48:49]
	v_pk_fma_f32 v[58:59], v[140:141], v[52:53], v[58:59] neg_lo:[0,0,1] neg_hi:[0,0,1]
	v_pk_fma_f32 v[56:57], v[142:143], v[54:55], v[56:57] neg_lo:[0,0,1] neg_hi:[0,0,1]
	v_pk_fma_f32 v[62:63], v[136:137], v[52:53], v[62:63]
	v_pk_fma_f32 v[60:61], v[138:139], v[54:55], v[60:61]
	v_cndmask_b32_e64 v55, v55, v57, s[8:9]
	v_cndmask_b32_e64 v54, v54, v56, s[8:9]
	v_cndmask_b32_e64 v53, v53, v59, s[8:9]
	v_cndmask_b32_e64 v52, v52, v58, s[8:9]
	v_cndmask_b32_e64 v51, v51, v61, s[8:9]
	v_cndmask_b32_e64 v50, v50, v60, s[8:9]
	v_cndmask_b32_e64 v49, v49, v63, s[8:9]
	v_cndmask_b32_e64 v48, v48, v62, s[8:9]
; __device__ __forceinline__ unsigned cvtpk(float lo, float hi) { f32x2 v = {lo, hi}; bf16x2_t b = __builtin_convertvector(v, bf16x2_t); return __builtin_bit_cast(unsigned, b); }
; #define PG8_LAS __attribute__((address_space(3)))
;     __device__ __forceinline__ void operator()(Acc& acc, const Unit& u, int wr, int wc, int fr, int fq, PG8_LAS unsigned char* ldx, const Pre&) const {
;     ...
;             for (int m = 0; m < 4; ++m) {
;                 const int rowl = ai * 128 + wr * 64 + m * 16 + fr;
;                 const size_t grow = (size_t)u.pm * 256 + rowl;
;                 const f32x4 cs = rc[m], sn = rs[m];
; #pragma unroll
;                 for (int bj = 0; bj < 2; ++bj) {
;                     const bool normed = bj == 0 ? normed0 : normed1;
;                     f32x4 v0 = acc[ai][bj][m][0], v1 = acc[ai][bj][m][1];
;                     if (normed) {
;                         const f32x2 pr = *(const PG8_LAS f32x2*)(X + (rowl * 2 + bj) * 4 + (wc & 2));
;                         const float rinv = rsqrtf((pr.x + pr.y) * (1.0f / 64.0f) + EPS);
;                         v0 = v0 * rinv * g0; v1 = v1 * rinv * g1;
;                         if (rope) { const f32x4 t0 = v0 * cs - v1 * sn, t1 = v0 * sn + v1 * cs; v0 = t0; v1 = t1; }
;                     }
;                     bf16_t* p = QKV + grow * INC + pn * 256 + bj * 128 + wc * 32 + ((fq & 1) ? 16 + 4 * (fq - 1) : 4 * fq);
;                     u32x2 w0, w1; w0.x = cvtpk(v0[0], v0[1]); w0.y = cvtpk(v0[2], v0[3]); w1.x = cvtpk(v1[0], v1[1]); w1.y = cvtpk(v1[2], v1[3]);
;                     *(u32x4*)p = pair16(w0, w1);
;                 }
.Lp2_norope_10:
.LBB0_473:
	v_cvt_pk_bf16_f32 v52, v52, v53
	v_cvt_pk_bf16_f32 v53, v54, v55
	v_cvt_pk_bf16_f32 v54, v48, v49
	v_cvt_pk_bf16_f32 v55, v50, v51
	s_nop 0
	v_permlane16_swap_b32_e32 v52, v54
	v_permlane16_swap_b32_e32 v53, v55
	global_store_dwordx4 v[64:65], v[52:55], off offset:256
	s_and_b64 vcc, exec, s[10:11]
	s_cbranch_vccnz .LBB0_475
	ds_read_b64 v[48:49], v225
	s_waitcnt lgkmcnt(0)
	v_add_f32_e32 v48, v48, v49
	v_fmamk_f32 v48, v48, 0x3c800000, v219
	v_rsq_f32_e32 v48, v48
	s_nop 0
	v_pk_mul_f32 v[42:43], v[42:43], v[48:49] op_sel_hi:[1,0]
	v_pk_mul_f32 v[40:41], v[40:41], v[48:49] op_sel_hi:[1,0]
	v_pk_mul_f32 v[46:47], v[46:47], v[48:49] op_sel_hi:[1,0]
	v_pk_mul_f32 v[44:45], v[44:45], v[48:49] op_sel_hi:[1,0]
	v_pk_mul_f32 v[40:41], v[164:165], v[40:41]
	v_pk_mul_f32 v[42:43], v[166:167], v[42:43]
	v_pk_mul_f32 v[44:45], v[160:161], v[44:45]
	v_pk_mul_f32 v[46:47], v[162:163], v[46:47]
	s_and_b64 vcc, exec, s[8:9]
	s_cbranch_vccz .Lp2_norope_11
	v_pk_mul_f32 v[48:49], v[114:115], v[42:43]
	v_pk_mul_f32 v[50:51], v[112:113], v[40:41]
	v_pk_mul_f32 v[52:53], v[118:119], v[42:43]
	v_pk_mul_f32 v[54:55], v[116:117], v[40:41]
	v_pk_fma_f32 v[50:51], v[116:117], v[44:45], v[50:51] neg_lo:[0,0,1] neg_hi:[0,0,1]
	v_pk_fma_f32 v[48:49], v[118:119], v[46:47], v[48:49] neg_lo:[0,0,1] neg_hi:[0,0,1]
	v_pk_fma_f32 v[54:55], v[112:113], v[44:45], v[54:55]
	v_pk_fma_f32 v[52:53], v[114:115], v[46:47], v[52:53]
	v_cndmask_b32_e64 v47, v47, v49, s[8:9]
	v_cndmask_b32_e64 v46, v46, v48, s[8:9]
	v_cndmask_b32_e64 v45, v45, v51, s[8:9]
	v_cndmask_b32_e64 v44, v44, v50, s[8:9]
	v_cndmask_b32_e64 v43, v43, v53, s[8:9]
	v_cndmask_b32_e64 v42, v42, v52, s[8:9]
	v_cndmask_b32_e64 v41, v41, v55, s[8:9]
	v_cndmask_b32_e64 v40, v40, v54, s[8:9]
.Lp2_norope_11:
.LBB0_475:
	v_lshl_add_u64 v[48:49], s[48:49], 0, v[186:187]
	v_mov_b64_e32 v[50:51], s[24:25]
	v_mad_u64_u32 v[50:51], s[46:47], v48, s79, v[50:51]
	v_mad_i32_i24 v51, v49, s79, v51
	v_lshl_add_u64 v[48:49], s[2:3], 1, v[50:51]
	v_lshl_add_u64 v[48:49], v[48:49], 0, s[36:37]
	v_cvt_pk_bf16_f32 v44, v44, v45
	v_cvt_pk_bf16_f32 v45, v46, v47
	v_cvt_pk_bf16_f32 v46, v40, v41
	v_cvt_pk_bf16_f32 v47, v42, v43
	v_lshl_add_u64 v[48:49], v[176:177], 1, v[48:49]
	v_permlane16_swap_b32_e32 v44, v46
	v_permlane16_swap_b32_e32 v45, v47
	s_and_b64 vcc, exec, s[12:13]
	global_store_dwordx4 v[48:49], v[44:47], off
	s_cbranch_vccnz .LBB0_477
	ds_read_b64 v[40:41], v225 offset:16
	s_waitcnt lgkmcnt(0)
	v_add_f32_e32 v40, v40, v41
	v_fmamk_f32 v40, v40, 0x3c800000, v219
	v_rsq_f32_e32 v40, v40
	s_nop 0
	v_pk_mul_f32 v[34:35], v[34:35], v[40:41] op_sel_hi:[1,0]
	v_pk_mul_f32 v[32:33], v[32:33], v[40:41] op_sel_hi:[1,0]
	v_pk_mul_f32 v[38:39], v[38:39], v[40:41] op_sel_hi:[1,0]
	v_pk_mul_f32 v[36:37], v[36:37], v[40:41] op_sel_hi:[1,0]
	v_pk_mul_f32 v[32:33], v[164:165], v[32:33]
	v_pk_mul_f32 v[34:35], v[166:167], v[34:35]
	v_pk_mul_f32 v[36:37], v[160:161], v[36:37]
	v_pk_mul_f32 v[38:39], v[162:163], v[38:39]
	s_and_b64 vcc, exec, s[8:9]
	s_cbranch_vccz .Lp2_norope_12
	v_pk_mul_f32 v[40:41], v[114:115], v[34:35]
	v_pk_mul_f32 v[42:43], v[112:113], v[32:33]
	v_pk_mul_f32 v[44:45], v[118:119], v[34:35]
	v_pk_mul_f32 v[46:47], v[116:117], v[32:33]
	v_pk_fma_f32 v[42:43], v[116:117], v[36:37], v[42:43] neg_lo:[0,0,1] neg_hi:[0,0,1]
	v_pk_fma_f32 v[40:41], v[118:119], v[38:39], v[40:41] neg_lo:[0,0,1] neg_hi:[0,0,1]
	v_pk_fma_f32 v[46:47], v[112:113], v[36:37], v[46:47]
	v_pk_fma_f32 v[44:45], v[114:115], v[38:39], v[44:45]
	v_cndmask_b32_e64 v39, v39, v41, s[8:9]
	v_cndmask_b32_e64 v38, v38, v40, s[8:9]
	v_cndmask_b32_e64 v37, v37, v43, s[8:9]
	v_cndmask_b32_e64 v36, v36, v42, s[8:9]
	v_cndmask_b32_e64 v35, v35, v45, s[8:9]
	v_cndmask_b32_e64 v34, v34, v44, s[8:9]
	v_cndmask_b32_e64 v33, v33, v47, s[8:9]
	v_cndmask_b32_e64 v32, v32, v46, s[8:9]
.Lp2_norope_12:
.LBB0_477:
	v_cvt_pk_bf16_f32 v36, v36, v37
	v_cvt_pk_bf16_f32 v37, v38, v39
	v_cvt_pk_bf16_f32 v38, v32, v33
	v_cvt_pk_bf16_f32 v39, v34, v35
	s_nop 0
	v_permlane16_swap_b32_e32 v36, v38
	v_permlane16_swap_b32_e32 v37, v39
	global_store_dwordx4 v[48:49], v[36:39], off offset:256
	s_and_b64 vcc, exec, s[10:11]
	s_cbranch_vccnz .LBB0_479
	ds_read_b64 v[32:33], v226
	s_waitcnt lgkmcnt(0)
	v_add_f32_e32 v32, v32, v33
	v_fmamk_f32 v32, v32, 0x3c800000, v219
	v_rsq_f32_e32 v32, v32
	s_nop 0
	v_pk_mul_f32 v[26:27], v[26:27], v[32:33] op_sel_hi:[1,0]
	v_pk_mul_f32 v[24:25], v[24:25], v[32:33] op_sel_hi:[1,0]
	v_pk_mul_f32 v[30:31], v[30:31], v[32:33] op_sel_hi:[1,0]
	v_pk_mul_f32 v[28:29], v[28:29], v[32:33] op_sel_hi:[1,0]
	v_pk_mul_f32 v[24:25], v[164:165], v[24:25]
	v_pk_mul_f32 v[26:27], v[166:167], v[26:27]
	v_pk_mul_f32 v[28:29], v[160:161], v[28:29]
	v_pk_mul_f32 v[30:31], v[162:163], v[30:31]
	s_and_b64 vcc, exec, s[8:9]
	s_cbranch_vccz .Lp2_norope_13
	v_pk_mul_f32 v[32:33], v[90:91], v[26:27]
	v_pk_mul_f32 v[34:35], v[88:89], v[24:25]
	v_pk_mul_f32 v[36:37], v[94:95], v[26:27]
	v_pk_mul_f32 v[38:39], v[92:93], v[24:25]
	v_pk_fma_f32 v[34:35], v[92:93], v[28:29], v[34:35] neg_lo:[0,0,1] neg_hi:[0,0,1]
	v_pk_fma_f32 v[32:33], v[94:95], v[30:31], v[32:33] neg_lo:[0,0,1] neg_hi:[0,0,1]
	v_pk_fma_f32 v[38:39], v[88:89], v[28:29], v[38:39]
	v_pk_fma_f32 v[36:37], v[90:91], v[30:31], v[36:37]
	v_cndmask_b32_e64 v31, v31, v33, s[8:9]
	v_cndmask_b32_e64 v30, v30, v32, s[8:9]
	v_cndmask_b32_e64 v29, v29, v35, s[8:9]
	v_cndmask_b32_e64 v28, v28, v34, s[8:9]
	v_cndmask_b32_e64 v27, v27, v37, s[8:9]
	v_cndmask_b32_e64 v26, v26, v36, s[8:9]
	v_cndmask_b32_e64 v25, v25, v39, s[8:9]
	v_cndmask_b32_e64 v24, v24, v38, s[8:9]
; __device__ __forceinline__ unsigned cvtpk(float lo, float hi) { f32x2 v = {lo, hi}; bf16x2_t b = __builtin_convertvector(v, bf16x2_t); return __builtin_bit_cast(unsigned, b); }
; #define PG8_LAS __attribute__((address_space(3)))
;     __device__ __forceinline__ void operator()(Acc& acc, const Unit& u, int wr, int wc, int fr, int fq, PG8_LAS unsigned char* ldx, const Pre&) const {
;     ...
;             for (int m = 0; m < 4; ++m) {
;                 const int rowl = ai * 128 + wr * 64 + m * 16 + fr;
;                 const size_t grow = (size_t)u.pm * 256 + rowl;
;                 const f32x4 cs = rc[m], sn = rs[m];
; #pragma unroll
;                 for (int bj = 0; bj < 2; ++bj) {
;                     const bool normed = bj == 0 ? normed0 : normed1;
;                     f32x4 v0 = acc[ai][bj][m][0], v1 = acc[ai][bj][m][1];
;                     if (normed) {
;                         const f32x2 pr = *(const PG8_LAS f32x2*)(X + (rowl * 2 + bj) * 4 + (wc & 2));
;                         const float rinv = rsqrtf((pr.x + pr.y) * (1.0f / 64.0f) + EPS);
;                         v0 = v0 * rinv * g0; v1 = v1 * rinv * g1;
;                         if (rope) { const f32x4 t0 = v0 * cs - v1 * sn, t1 = v0 * sn + v1 * cs; v0 = t0; v1 = t1; }
;                     }
;                     bf16_t* p = QKV + grow * INC + pn * 256 + bj * 128 + wc * 32 + ((fq & 1) ? 16 + 4 * (fq - 1) : 4 * fq);
;                     u32x2 w0, w1; w0.x = cvtpk(v0[0], v0[1]); w0.y = cvtpk(v0[2], v0[3]); w1.x = cvtpk(v1[0], v1[1]); w1.y = cvtpk(v1[2], v1[3]);
;                     *(u32x4*)p = pair16(w0, w1);
;                 }
;                 asm volatile("" ::: "memory");
;             }
;         }
.Lp2_norope_13:
.LBB0_479:
	v_lshl_add_u64 v[32:33], s[48:49], 0, v[188:189]
	v_mov_b64_e32 v[34:35], s[24:25]
	v_mad_u64_u32 v[34:35], s[46:47], v32, s79, v[34:35]
	v_mad_i32_i24 v35, v33, s79, v35
	v_lshl_add_u64 v[32:33], s[2:3], 1, v[34:35]
	v_lshl_add_u64 v[32:33], v[32:33], 0, s[36:37]
	v_cvt_pk_bf16_f32 v28, v28, v29
	v_cvt_pk_bf16_f32 v29, v30, v31
	v_cvt_pk_bf16_f32 v30, v24, v25
	v_cvt_pk_bf16_f32 v31, v26, v27
	v_lshl_add_u64 v[32:33], v[176:177], 1, v[32:33]
	v_permlane16_swap_b32_e32 v28, v30
	v_permlane16_swap_b32_e32 v29, v31
	s_and_b64 vcc, exec, s[12:13]
	global_store_dwordx4 v[32:33], v[28:31], off
	s_cbranch_vccnz .LBB0_481
	ds_read_b64 v[24:25], v226 offset:16
	s_waitcnt lgkmcnt(0)
	v_add_f32_e32 v24, v24, v25
	v_fmamk_f32 v24, v24, 0x3c800000, v219
	v_rsq_f32_e32 v24, v24
	s_nop 0
	v_pk_mul_f32 v[18:19], v[18:19], v[24:25] op_sel_hi:[1,0]
	v_pk_mul_f32 v[16:17], v[16:17], v[24:25] op_sel_hi:[1,0]
	v_pk_mul_f32 v[22:23], v[22:23], v[24:25] op_sel_hi:[1,0]
	v_pk_mul_f32 v[20:21], v[20:21], v[24:25] op_sel_hi:[1,0]
	v_pk_mul_f32 v[16:17], v[164:165], v[16:17]
	v_pk_mul_f32 v[18:19], v[166:167], v[18:19]
	v_pk_mul_f32 v[20:21], v[160:161], v[20:21]
	v_pk_mul_f32 v[22:23], v[162:163], v[22:23]
	s_and_b64 vcc, exec, s[8:9]
	s_cbranch_vccz .Lp2_norope_14
	v_pk_mul_f32 v[24:25], v[90:91], v[18:19]
	v_pk_mul_f32 v[26:27], v[88:89], v[16:17]
	v_pk_mul_f32 v[28:29], v[94:95], v[18:19]
	v_pk_mul_f32 v[30:31], v[92:93], v[16:17]
	v_pk_fma_f32 v[26:27], v[92:93], v[20:21], v[26:27] neg_lo:[0,0,1] neg_hi:[0,0,1]
	v_pk_fma_f32 v[24:25], v[94:95], v[22:23], v[24:25] neg_lo:[0,0,1] neg_hi:[0,0,1]
	v_pk_fma_f32 v[30:31], v[88:89], v[20:21], v[30:31]
	v_pk_fma_f32 v[28:29], v[90:91], v[22:23], v[28:29]
	v_cndmask_b32_e64 v23, v23, v25, s[8:9]
	v_cndmask_b32_e64 v22, v22, v24, s[8:9]
	v_cndmask_b32_e64 v21, v21, v27, s[8:9]
	v_cndmask_b32_e64 v20, v20, v26, s[8:9]
	v_cndmask_b32_e64 v19, v19, v29, s[8:9]
	v_cndmask_b32_e64 v18, v18, v28, s[8:9]
	v_cndmask_b32_e64 v17, v17, v31, s[8:9]
	v_cndmask_b32_e64 v16, v16, v30, s[8:9]
.Lp2_norope_14:
.LBB0_481:
	v_cvt_pk_bf16_f32 v20, v20, v21
	v_cvt_pk_bf16_f32 v21, v22, v23
	v_cvt_pk_bf16_f32 v22, v16, v17
	v_cvt_pk_bf16_f32 v23, v18, v19
	s_nop 0
	v_permlane16_swap_b32_e32 v20, v22
	v_permlane16_swap_b32_e32 v21, v23
	global_store_dwordx4 v[32:33], v[20:23], off offset:256
	s_and_b64 vcc, exec, s[10:11]
	s_cbranch_vccnz .LBB0_483
	ds_read_b64 v[16:17], v227
	s_waitcnt lgkmcnt(0)
	v_add_f32_e32 v16, v16, v17
	v_fmamk_f32 v16, v16, 0x3c800000, v219
	v_rsq_f32_e32 v16, v16
	s_nop 0
	v_pk_mul_f32 v[10:11], v[10:11], v[16:17] op_sel_hi:[1,0]
	v_pk_mul_f32 v[8:9], v[8:9], v[16:17] op_sel_hi:[1,0]
	v_pk_mul_f32 v[14:15], v[14:15], v[16:17] op_sel_hi:[1,0]
	v_pk_mul_f32 v[12:13], v[12:13], v[16:17] op_sel_hi:[1,0]
	v_pk_mul_f32 v[8:9], v[164:165], v[8:9]
	v_pk_mul_f32 v[10:11], v[166:167], v[10:11]
	v_pk_mul_f32 v[12:13], v[160:161], v[12:13]
	v_pk_mul_f32 v[14:15], v[162:163], v[14:15]
	s_and_b64 vcc, exec, s[8:9]
	s_cbranch_vccz .Lp2_norope_15
	v_pk_mul_f32 v[16:17], v[204:205], v[10:11]
	v_pk_mul_f32 v[18:19], v[202:203], v[8:9]
	v_pk_mul_f32 v[20:21], v[208:209], v[10:11]
	v_pk_mul_f32 v[22:23], v[206:207], v[8:9]
	v_pk_fma_f32 v[18:19], v[206:207], v[12:13], v[18:19] neg_lo:[0,0,1] neg_hi:[0,0,1]
	v_pk_fma_f32 v[16:17], v[208:209], v[14:15], v[16:17] neg_lo:[0,0,1] neg_hi:[0,0,1]
	v_pk_fma_f32 v[22:23], v[202:203], v[12:13], v[22:23]
	v_pk_fma_f32 v[20:21], v[204:205], v[14:15], v[20:21]
	v_cndmask_b32_e64 v15, v15, v17, s[8:9]
	v_cndmask_b32_e64 v14, v14, v16, s[8:9]
	v_cndmask_b32_e64 v13, v13, v19, s[8:9]
	v_cndmask_b32_e64 v12, v12, v18, s[8:9]
	v_cndmask_b32_e64 v11, v11, v21, s[8:9]
	v_cndmask_b32_e64 v10, v10, v20, s[8:9]
	v_cndmask_b32_e64 v9, v9, v23, s[8:9]
	v_cndmask_b32_e64 v8, v8, v22, s[8:9]
.Lp2_norope_15:
.LBB0_483:
	v_lshl_add_u64 v[16:17], s[48:49], 0, v[190:191]
	v_mov_b64_e32 v[18:19], s[24:25]
	v_mad_u64_u32 v[18:19], s[10:11], v16, s79, v[18:19]
	v_mad_i32_i24 v19, v17, s79, v19
	v_lshl_add_u64 v[16:17], s[2:3], 1, v[18:19]
	v_lshl_add_u64 v[16:17], v[16:17], 0, s[36:37]
	v_cvt_pk_bf16_f32 v12, v12, v13
	v_cvt_pk_bf16_f32 v13, v14, v15
	v_cvt_pk_bf16_f32 v14, v8, v9
	v_cvt_pk_bf16_f32 v15, v10, v11
	v_lshl_add_u64 v[16:17], v[176:177], 1, v[16:17]
	v_permlane16_swap_b32_e32 v12, v14
	v_permlane16_swap_b32_e32 v13, v15
	s_and_b64 vcc, exec, s[12:13]
	global_store_dwordx4 v[16:17], v[12:15], off
	s_cbranch_vccnz .LBB0_485
	ds_read_b64 v[8:9], v227 offset:16
	s_waitcnt lgkmcnt(0)
	v_add_f32_e32 v8, v8, v9
	v_fmamk_f32 v8, v8, 0x3c800000, v219
	v_rsq_f32_e32 v8, v8
	s_nop 0
	v_pk_mul_f32 v[2:3], v[2:3], v[8:9] op_sel_hi:[1,0]
	v_pk_mul_f32 v[0:1], v[0:1], v[8:9] op_sel_hi:[1,0]
	v_pk_mul_f32 v[6:7], v[6:7], v[8:9] op_sel_hi:[1,0]
	v_pk_mul_f32 v[4:5], v[4:5], v[8:9] op_sel_hi:[1,0]
	v_pk_mul_f32 v[0:1], v[164:165], v[0:1]
	v_pk_mul_f32 v[2:3], v[166:167], v[2:3]
	v_pk_mul_f32 v[4:5], v[160:161], v[4:5]
	v_pk_mul_f32 v[6:7], v[162:163], v[6:7]
	s_and_b64 vcc, exec, s[8:9]
	s_cbranch_vccz .Lp2_norope_16
	v_pk_mul_f32 v[8:9], v[204:205], v[2:3]
	v_pk_mul_f32 v[10:11], v[202:203], v[0:1]
	v_pk_mul_f32 v[12:13], v[208:209], v[2:3]
	v_pk_mul_f32 v[14:15], v[206:207], v[0:1]
	v_pk_fma_f32 v[10:11], v[206:207], v[4:5], v[10:11] neg_lo:[0,0,1] neg_hi:[0,0,1]
	v_pk_fma_f32 v[8:9], v[208:209], v[6:7], v[8:9] neg_lo:[0,0,1] neg_hi:[0,0,1]
	v_pk_fma_f32 v[14:15], v[202:203], v[4:5], v[14:15]
	v_pk_fma_f32 v[12:13], v[204:205], v[6:7], v[12:13]
	v_cndmask_b32_e64 v7, v7, v9, s[8:9]
	v_cndmask_b32_e64 v6, v6, v8, s[8:9]
	v_cndmask_b32_e64 v5, v5, v11, s[8:9]
	v_cndmask_b32_e64 v4, v4, v10, s[8:9]
	v_cndmask_b32_e64 v3, v3, v13, s[8:9]
	v_cndmask_b32_e64 v2, v2, v12, s[8:9]
	v_cndmask_b32_e64 v1, v1, v15, s[8:9]
	v_cndmask_b32_e64 v0, v0, v14, s[8:9]
.Lp2_norope_16:
.LBB0_485:
	v_cvt_pk_bf16_f32 v4, v4, v5
	v_cvt_pk_bf16_f32 v5, v6, v7
	v_cvt_pk_bf16_f32 v6, v0, v1
	v_cvt_pk_bf16_f32 v7, v2, v3
	s_nop 0
	v_permlane16_swap_b32_e32 v4, v6
	v_permlane16_swap_b32_e32 v5, v7
	global_store_dwordx4 v[16:17], v[4:7], off offset:256
	s_andn2_b64 vcc, exec, s[40:41]
	s_mov_b64 s[2:3], -1
	s_cbranch_vccnz .LBB0_382
	s_and_b64 vcc, exec, s[4:5]
	s_cbranch_vccnz .LBB0_381
	s_barrier
	s_branch .LBB0_381

; __device__ __forceinline__ unsigned cvtpk(float lo, float hi) { f32x2 v = {lo, hi}; bf16x2_t b = __builtin_convertvector(v, bf16x2_t); return __builtin_bit_cast(unsigned, b); }
; #define PG8_LAS __attribute__((address_space(3)))
;     __device__ __forceinline__ void operator()(Acc& acc, const Unit& u, int wr, int wc, int fr, int fq, PG8_LAS unsigned char*, const Pre& P) const {
;         const int col0 = u.pn * 128 + wc * 32 + 8 * fq;
; #pragma unroll
;         for (int ai = 0; ai < 2; ++ai)
; #pragma unroll
;             for (int m = 0; m < 4; ++m) {
;                 const int row = u.pm * 256 + ai * 128 + wr * 64 + m * 16 + fr;
;                 const float r2 = rsqrtf(P.r2[ai][m] * (1.0f / DM) + EPS);
;                 float h[8];
; #pragma unroll
;                 for (int n = 0; n < 2; ++n)
; #pragma unroll
;                     for (int j = 0; j < 4; ++j) { const float g = acc[ai][0][m][n][j] * r2 + P.bg[n][j], up = acc[ai][1][m][n][j] * r2 + P.bu[n][j];
;                         h[n * 4 + j] = g * __builtin_amdgcn_rcpf(1.0f + __builtin_amdgcn_exp2f(-g * LOG2E)) * up; }
;                 u32x4 w; w.x = cvtpk(h[0], h[1]); w.y = cvtpk(h[2], h[3]); w.z = cvtpk(h[4], h[5]); w.w = cvtpk(h[6], h[7]);
;                 *(u32x4*)(HID + (size_t)row * FFH + col0) = w;
;             }
;     }
.LBB0_947:
	v_lshl_add_u32 v236, s53, 7, v164
	v_lshl_add_u32 v237, s24, 8, v162
	v_ashrrev_i32_e32 v239, 31, v236
	v_mov_b32_e32 v238, v236
	v_mov_b64_e32 v[232:233], s[12:13]
	v_mad_i64_i32 v[232:233], s[26:27], v237, s52, v[232:233]
	v_lshlrev_b64 v[238:239], 1, v[238:239]
	v_mov_b32_e32 v178, 0xbfb8aa3b
	s_mov_b32 s62, 0x16000
	s_mov_b32 s63, 0
	s_mov_b32 s66, 0x6e000
	s_mov_b32 s67, 0
	v_lshl_add_u64 v[232:233], v[232:233], 0, v[238:239]
	v_fmamk_f32 v176, v174, 0x3a800000, v166
	v_rsq_f32_e32 v176, v176
	s_nop 0
	v_pk_fma_f32 v[180:181], v[176:177], v[140:141], v[12:13] op_sel_hi:[0,1,1]
	v_pk_fma_f32 v[182:183], v[176:177], v[142:143], v[14:15] op_sel_hi:[0,1,1]
	v_pk_fma_f32 v[184:185], v[176:177], v[136:137], v[4:5] op_sel_hi:[0,1,1]
	v_pk_fma_f32 v[186:187], v[176:177], v[138:139], v[6:7] op_sel_hi:[0,1,1]
	v_pk_fma_f32 v[188:189], v[176:177], v[132:133], v[8:9] op_sel_hi:[0,1,1]
	v_pk_fma_f32 v[190:191], v[176:177], v[134:135], v[10:11] op_sel_hi:[0,1,1]
	v_pk_fma_f32 v[192:193], v[176:177], v[128:129], v[0:1] op_sel_hi:[0,1,1]
	v_pk_fma_f32 v[194:195], v[176:177], v[130:131], v[2:3] op_sel_hi:[0,1,1]
	v_pk_mul_f32 v[196:197], v[180:181], v[178:179] op_sel_hi:[1,0]
	v_pk_mul_f32 v[198:199], v[182:183], v[178:179] op_sel_hi:[1,0]
	v_pk_mul_f32 v[200:201], v[184:185], v[178:179] op_sel_hi:[1,0]
	v_pk_mul_f32 v[202:203], v[186:187], v[178:179] op_sel_hi:[1,0]
	v_exp_f32_e32 v196, v196
	v_exp_f32_e32 v197, v197
	v_exp_f32_e32 v198, v198
	v_exp_f32_e32 v199, v199
	v_exp_f32_e32 v200, v200
	v_exp_f32_e32 v201, v201
	v_exp_f32_e32 v202, v202
	v_exp_f32_e32 v203, v203
	v_pk_add_f32 v[196:197], v[196:197], 1.0 op_sel_hi:[1,0]
	v_pk_add_f32 v[198:199], v[198:199], 1.0 op_sel_hi:[1,0]
	v_pk_add_f32 v[200:201], v[200:201], 1.0 op_sel_hi:[1,0]
	v_pk_add_f32 v[202:203], v[202:203], 1.0 op_sel_hi:[1,0]
	v_rcp_f32_e32 v196, v196
	v_rcp_f32_e32 v197, v197
	v_rcp_f32_e32 v198, v198
	v_rcp_f32_e32 v199, v199
	v_rcp_f32_e32 v200, v200
	v_rcp_f32_e32 v201, v201
	v_rcp_f32_e32 v202, v202
	v_rcp_f32_e32 v203, v203
	v_pk_mul_f32 v[180:181], v[180:181], v[196:197]
	v_pk_mul_f32 v[182:183], v[182:183], v[198:199]
	v_pk_mul_f32 v[184:185], v[184:185], v[200:201]
	v_pk_mul_f32 v[186:187], v[186:187], v[202:203]
	v_pk_mul_f32 v[180:181], v[180:181], v[188:189]
	v_pk_mul_f32 v[182:183], v[182:183], v[190:191]
	v_pk_mul_f32 v[184:185], v[184:185], v[192:193]
	v_pk_mul_f32 v[186:187], v[186:187], v[194:195]
	v_cvt_pk_bf16_f32 v244, v180, v181
	v_cvt_pk_bf16_f32 v245, v182, v183
	v_cvt_pk_bf16_f32 v246, v184, v185
	v_cvt_pk_bf16_f32 v247, v186, v187
	global_store_dwordx4 v[232:233], v[244:247], off
	v_lshl_add_u64 v[232:233], v[232:233], 0, s[62:63]
	v_fmamk_f32 v204, v173, 0x3a800000, v166
	v_rsq_f32_e32 v204, v204
	s_nop 0
	v_pk_fma_f32 v[208:209], v[204:205], v[124:125], v[12:13] op_sel_hi:[0,1,1]
	v_pk_fma_f32 v[210:211], v[204:205], v[126:127], v[14:15] op_sel_hi:[0,1,1]
	v_pk_fma_f32 v[212:213], v[204:205], v[120:121], v[4:5] op_sel_hi:[0,1,1]
	v_pk_fma_f32 v[214:215], v[204:205], v[122:123], v[6:7] op_sel_hi:[0,1,1]
	v_pk_fma_f32 v[216:217], v[204:205], v[116:117], v[8:9] op_sel_hi:[0,1,1]
	v_pk_fma_f32 v[218:219], v[204:205], v[118:119], v[10:11] op_sel_hi:[0,1,1]
	v_pk_fma_f32 v[220:221], v[204:205], v[112:113], v[0:1] op_sel_hi:[0,1,1]
	v_pk_fma_f32 v[222:223], v[204:205], v[114:115], v[2:3] op_sel_hi:[0,1,1]
	v_pk_mul_f32 v[224:225], v[208:209], v[178:179] op_sel_hi:[1,0]
	v_pk_mul_f32 v[226:227], v[210:211], v[178:179] op_sel_hi:[1,0]
	v_pk_mul_f32 v[228:229], v[212:213], v[178:179] op_sel_hi:[1,0]
	v_pk_mul_f32 v[230:231], v[214:215], v[178:179] op_sel_hi:[1,0]
	v_exp_f32_e32 v224, v224
	v_exp_f32_e32 v225, v225
	v_exp_f32_e32 v226, v226
	v_exp_f32_e32 v227, v227
	v_exp_f32_e32 v228, v228
	v_exp_f32_e32 v229, v229
	v_exp_f32_e32 v230, v230
	v_exp_f32_e32 v231, v231
	v_pk_add_f32 v[224:225], v[224:225], 1.0 op_sel_hi:[1,0]
	v_pk_add_f32 v[226:227], v[226:227], 1.0 op_sel_hi:[1,0]
	v_pk_add_f32 v[228:229], v[228:229], 1.0 op_sel_hi:[1,0]
	v_pk_add_f32 v[230:231], v[230:231], 1.0 op_sel_hi:[1,0]
	v_rcp_f32_e32 v224, v224
	v_rcp_f32_e32 v225, v225
	v_rcp_f32_e32 v226, v226
	v_rcp_f32_e32 v227, v227
	v_rcp_f32_e32 v228, v228
	v_rcp_f32_e32 v229, v229
	v_rcp_f32_e32 v230, v230
	v_rcp_f32_e32 v231, v231
	v_pk_mul_f32 v[208:209], v[208:209], v[224:225]
	v_pk_mul_f32 v[210:211], v[210:211], v[226:227]
	v_pk_mul_f32 v[212:213], v[212:213], v[228:229]
	v_pk_mul_f32 v[214:215], v[214:215], v[230:231]
	v_pk_mul_f32 v[208:209], v[208:209], v[216:217]
	v_pk_mul_f32 v[210:211], v[210:211], v[218:219]
	v_pk_mul_f32 v[212:213], v[212:213], v[220:221]
	v_pk_mul_f32 v[214:215], v[214:215], v[222:223]
	v_cvt_pk_bf16_f32 v248, v208, v209
	v_cvt_pk_bf16_f32 v249, v210, v211
	v_cvt_pk_bf16_f32 v250, v212, v213
	v_cvt_pk_bf16_f32 v251, v214, v215
	global_store_dwordx4 v[232:233], v[248:251], off
	v_lshl_add_u64 v[232:233], v[232:233], 0, s[62:63]
	v_fmamk_f32 v176, v172, 0x3a800000, v166
	v_rsq_f32_e32 v176, v176
	s_nop 0
	v_pk_fma_f32 v[180:181], v[176:177], v[108:109], v[12:13] op_sel_hi:[0,1,1]
	v_pk_fma_f32 v[182:183], v[176:177], v[110:111], v[14:15] op_sel_hi:[0,1,1]
	v_pk_fma_f32 v[184:185], v[176:177], v[104:105], v[4:5] op_sel_hi:[0,1,1]
	v_pk_fma_f32 v[186:187], v[176:177], v[106:107], v[6:7] op_sel_hi:[0,1,1]
	v_pk_fma_f32 v[188:189], v[176:177], v[100:101], v[8:9] op_sel_hi:[0,1,1]
	v_pk_fma_f32 v[190:191], v[176:177], v[102:103], v[10:11] op_sel_hi:[0,1,1]
	v_pk_fma_f32 v[192:193], v[176:177], v[96:97], v[0:1] op_sel_hi:[0,1,1]
	v_pk_fma_f32 v[194:195], v[176:177], v[98:99], v[2:3] op_sel_hi:[0,1,1]
	v_pk_mul_f32 v[196:197], v[180:181], v[178:179] op_sel_hi:[1,0]
; __device__ __forceinline__ unsigned cvtpk(float lo, float hi) { f32x2 v = {lo, hi}; bf16x2_t b = __builtin_convertvector(v, bf16x2_t); return __builtin_bit_cast(unsigned, b); }
; #define PG8_LAS __attribute__((address_space(3)))
;     __device__ __forceinline__ void operator()(Acc& acc, const Unit& u, int wr, int wc, int fr, int fq, PG8_LAS unsigned char*, const Pre& P) const {
;         const int col0 = u.pn * 128 + wc * 32 + 8 * fq;
; #pragma unroll
;         for (int ai = 0; ai < 2; ++ai)
; #pragma unroll
;             for (int m = 0; m < 4; ++m) {
;                 const int row = u.pm * 256 + ai * 128 + wr * 64 + m * 16 + fr;
;                 const float r2 = rsqrtf(P.r2[ai][m] * (1.0f / DM) + EPS);
;                 float h[8];
; #pragma unroll
;                 for (int n = 0; n < 2; ++n)
; #pragma unroll
;                     for (int j = 0; j < 4; ++j) { const float g = acc[ai][0][m][n][j] * r2 + P.bg[n][j], up = acc[ai][1][m][n][j] * r2 + P.bu[n][j];
;                         h[n * 4 + j] = g * __builtin_amdgcn_rcpf(1.0f + __builtin_amdgcn_exp2f(-g * LOG2E)) * up; }
;                 u32x4 w; w.x = cvtpk(h[0], h[1]); w.y = cvtpk(h[2], h[3]); w.z = cvtpk(h[4], h[5]); w.w = cvtpk(h[6], h[7]);
;                 *(u32x4*)(HID + (size_t)row * FFH + col0) = w;
;             }
;     }
	v_pk_mul_f32 v[198:199], v[182:183], v[178:179] op_sel_hi:[1,0]
	v_pk_mul_f32 v[200:201], v[184:185], v[178:179] op_sel_hi:[1,0]
	v_pk_mul_f32 v[202:203], v[186:187], v[178:179] op_sel_hi:[1,0]
	v_exp_f32_e32 v196, v196
	v_exp_f32_e32 v197, v197
	v_exp_f32_e32 v198, v198
	v_exp_f32_e32 v199, v199
	v_exp_f32_e32 v200, v200
	v_exp_f32_e32 v201, v201
	v_exp_f32_e32 v202, v202
	v_exp_f32_e32 v203, v203
	v_pk_add_f32 v[196:197], v[196:197], 1.0 op_sel_hi:[1,0]
	v_pk_add_f32 v[198:199], v[198:199], 1.0 op_sel_hi:[1,0]
	v_pk_add_f32 v[200:201], v[200:201], 1.0 op_sel_hi:[1,0]
	v_pk_add_f32 v[202:203], v[202:203], 1.0 op_sel_hi:[1,0]
	v_rcp_f32_e32 v196, v196
	v_rcp_f32_e32 v197, v197
	v_rcp_f32_e32 v198, v198
	v_rcp_f32_e32 v199, v199
	v_rcp_f32_e32 v200, v200
	v_rcp_f32_e32 v201, v201
	v_rcp_f32_e32 v202, v202
	v_rcp_f32_e32 v203, v203
	v_pk_mul_f32 v[180:181], v[180:181], v[196:197]
	v_pk_mul_f32 v[182:183], v[182:183], v[198:199]
	v_pk_mul_f32 v[184:185], v[184:185], v[200:201]
	v_pk_mul_f32 v[186:187], v[186:187], v[202:203]
	v_pk_mul_f32 v[180:181], v[180:181], v[188:189]
	v_pk_mul_f32 v[182:183], v[182:183], v[190:191]
	v_pk_mul_f32 v[184:185], v[184:185], v[192:193]
	v_pk_mul_f32 v[186:187], v[186:187], v[194:195]
	v_cvt_pk_bf16_f32 v244, v180, v181
	v_cvt_pk_bf16_f32 v245, v182, v183
	v_cvt_pk_bf16_f32 v246, v184, v185
	v_cvt_pk_bf16_f32 v247, v186, v187
	global_store_dwordx4 v[232:233], v[244:247], off
	v_lshl_add_u64 v[232:233], v[232:233], 0, s[62:63]
	v_fmamk_f32 v204, v171, 0x3a800000, v166
	v_rsq_f32_e32 v204, v204
	s_nop 0
	v_pk_fma_f32 v[208:209], v[204:205], v[92:93], v[12:13] op_sel_hi:[0,1,1]
	v_pk_fma_f32 v[210:211], v[204:205], v[94:95], v[14:15] op_sel_hi:[0,1,1]
	v_pk_fma_f32 v[212:213], v[204:205], v[88:89], v[4:5] op_sel_hi:[0,1,1]
	v_pk_fma_f32 v[214:215], v[204:205], v[90:91], v[6:7] op_sel_hi:[0,1,1]
	v_pk_fma_f32 v[216:217], v[204:205], v[84:85], v[8:9] op_sel_hi:[0,1,1]
	v_pk_fma_f32 v[218:219], v[204:205], v[86:87], v[10:11] op_sel_hi:[0,1,1]
	v_pk_fma_f32 v[220:221], v[204:205], v[80:81], v[0:1] op_sel_hi:[0,1,1]
	v_pk_fma_f32 v[222:223], v[204:205], v[82:83], v[2:3] op_sel_hi:[0,1,1]
	v_pk_mul_f32 v[224:225], v[208:209], v[178:179] op_sel_hi:[1,0]
	v_pk_mul_f32 v[226:227], v[210:211], v[178:179] op_sel_hi:[1,0]
	v_pk_mul_f32 v[228:229], v[212:213], v[178:179] op_sel_hi:[1,0]
	v_pk_mul_f32 v[230:231], v[214:215], v[178:179] op_sel_hi:[1,0]
	v_exp_f32_e32 v224, v224
	v_exp_f32_e32 v225, v225
	v_exp_f32_e32 v226, v226
	v_exp_f32_e32 v227, v227
	v_exp_f32_e32 v228, v228
	v_exp_f32_e32 v229, v229
	v_exp_f32_e32 v230, v230
	v_exp_f32_e32 v231, v231
	v_pk_add_f32 v[224:225], v[224:225], 1.0 op_sel_hi:[1,0]
	v_pk_add_f32 v[226:227], v[226:227], 1.0 op_sel_hi:[1,0]
	v_pk_add_f32 v[228:229], v[228:229], 1.0 op_sel_hi:[1,0]
	v_pk_add_f32 v[230:231], v[230:231], 1.0 op_sel_hi:[1,0]
	v_rcp_f32_e32 v224, v224
	v_rcp_f32_e32 v225, v225
	v_rcp_f32_e32 v226, v226
	v_rcp_f32_e32 v227, v227
	v_rcp_f32_e32 v228, v228
	v_rcp_f32_e32 v229, v229
	v_rcp_f32_e32 v230, v230
	v_rcp_f32_e32 v231, v231
	v_pk_mul_f32 v[208:209], v[208:209], v[224:225]
	v_pk_mul_f32 v[210:211], v[210:211], v[226:227]
	v_pk_mul_f32 v[212:213], v[212:213], v[228:229]
	v_pk_mul_f32 v[214:215], v[214:215], v[230:231]
	v_pk_mul_f32 v[208:209], v[208:209], v[216:217]
	v_pk_mul_f32 v[210:211], v[210:211], v[218:219]
	v_pk_mul_f32 v[212:213], v[212:213], v[220:221]
	v_pk_mul_f32 v[214:215], v[214:215], v[222:223]
	v_cvt_pk_bf16_f32 v248, v208, v209
	v_cvt_pk_bf16_f32 v249, v210, v211
	v_cvt_pk_bf16_f32 v250, v212, v213
	v_cvt_pk_bf16_f32 v251, v214, v215
	global_store_dwordx4 v[232:233], v[248:251], off
	v_lshl_add_u64 v[232:233], v[232:233], 0, s[66:67]
	v_fmamk_f32 v176, v170, 0x3a800000, v166
	v_rsq_f32_e32 v176, v176
	s_nop 0
	v_pk_fma_f32 v[180:181], v[176:177], v[76:77], v[12:13] op_sel_hi:[0,1,1]
	v_pk_fma_f32 v[182:183], v[176:177], v[78:79], v[14:15] op_sel_hi:[0,1,1]
	v_pk_fma_f32 v[184:185], v[176:177], v[72:73], v[4:5] op_sel_hi:[0,1,1]
	v_pk_fma_f32 v[186:187], v[176:177], v[74:75], v[6:7] op_sel_hi:[0,1,1]
	v_pk_fma_f32 v[188:189], v[176:177], v[68:69], v[8:9] op_sel_hi:[0,1,1]
	v_pk_fma_f32 v[190:191], v[176:177], v[70:71], v[10:11] op_sel_hi:[0,1,1]
	v_pk_fma_f32 v[192:193], v[176:177], v[64:65], v[0:1] op_sel_hi:[0,1,1]
	v_pk_fma_f32 v[194:195], v[176:177], v[66:67], v[2:3] op_sel_hi:[0,1,1]
	v_pk_mul_f32 v[196:197], v[180:181], v[178:179] op_sel_hi:[1,0]
	v_pk_mul_f32 v[198:199], v[182:183], v[178:179] op_sel_hi:[1,0]
	v_pk_mul_f32 v[200:201], v[184:185], v[178:179] op_sel_hi:[1,0]
	v_pk_mul_f32 v[202:203], v[186:187], v[178:179] op_sel_hi:[1,0]
	v_exp_f32_e32 v196, v196
	v_exp_f32_e32 v197, v197
	v_exp_f32_e32 v198, v198
	v_exp_f32_e32 v199, v199
	v_exp_f32_e32 v200, v200
	v_exp_f32_e32 v201, v201
	v_exp_f32_e32 v202, v202
	v_exp_f32_e32 v203, v203
	v_pk_add_f32 v[196:197], v[196:197], 1.0 op_sel_hi:[1,0]
	v_pk_add_f32 v[198:199], v[198:199], 1.0 op_sel_hi:[1,0]
	v_pk_add_f32 v[200:201], v[200:201], 1.0 op_sel_hi:[1,0]
	v_pk_add_f32 v[202:203], v[202:203], 1.0 op_sel_hi:[1,0]
	v_rcp_f32_e32 v196, v196
	v_rcp_f32_e32 v197, v197
	v_rcp_f32_e32 v198, v198
	v_rcp_f32_e32 v199, v199
	v_rcp_f32_e32 v200, v200
	v_rcp_f32_e32 v201, v201
	v_rcp_f32_e32 v202, v202
	v_rcp_f32_e32 v203, v203
	v_pk_mul_f32 v[180:181], v[180:181], v[196:197]
	v_pk_mul_f32 v[182:183], v[182:183], v[198:199]
	v_pk_mul_f32 v[184:185], v[184:185], v[200:201]
	v_pk_mul_f32 v[186:187], v[186:187], v[202:203]
	v_pk_mul_f32 v[180:181], v[180:181], v[188:189]
	v_pk_mul_f32 v[182:183], v[182:183], v[190:191]
	v_pk_mul_f32 v[184:185], v[184:185], v[192:193]
	v_pk_mul_f32 v[186:187], v[186:187], v[194:195]
; __device__ __forceinline__ unsigned cvtpk(float lo, float hi) { f32x2 v = {lo, hi}; bf16x2_t b = __builtin_convertvector(v, bf16x2_t); return __builtin_bit_cast(unsigned, b); }
; #define PG8_LAS __attribute__((address_space(3)))
;     __device__ __forceinline__ void operator()(Acc& acc, const Unit& u, int wr, int wc, int fr, int fq, PG8_LAS unsigned char*, const Pre& P) const {
;         const int col0 = u.pn * 128 + wc * 32 + 8 * fq;
; #pragma unroll
;         for (int ai = 0; ai < 2; ++ai)
; #pragma unroll
;             for (int m = 0; m < 4; ++m) {
;                 const int row = u.pm * 256 + ai * 128 + wr * 64 + m * 16 + fr;
;                 const float r2 = rsqrtf(P.r2[ai][m] * (1.0f / DM) + EPS);
;                 float h[8];
; #pragma unroll
;                 for (int n = 0; n < 2; ++n)
; #pragma unroll
;                     for (int j = 0; j < 4; ++j) { const float g = acc[ai][0][m][n][j] * r2 + P.bg[n][j], up = acc[ai][1][m][n][j] * r2 + P.bu[n][j];
;                         h[n * 4 + j] = g * __builtin_amdgcn_rcpf(1.0f + __builtin_amdgcn_exp2f(-g * LOG2E)) * up; }
;                 u32x4 w; w.x = cvtpk(h[0], h[1]); w.y = cvtpk(h[2], h[3]); w.z = cvtpk(h[4], h[5]); w.w = cvtpk(h[6], h[7]);
;                 *(u32x4*)(HID + (size_t)row * FFH + col0) = w;
;             }
;     }
	v_cvt_pk_bf16_f32 v244, v180, v181
	v_cvt_pk_bf16_f32 v245, v182, v183
	v_cvt_pk_bf16_f32 v246, v184, v185
	v_cvt_pk_bf16_f32 v247, v186, v187
	global_store_dwordx4 v[232:233], v[244:247], off
	v_lshl_add_u64 v[232:233], v[232:233], 0, s[62:63]
	v_fmamk_f32 v204, v169, 0x3a800000, v166
	v_rsq_f32_e32 v204, v204
	s_nop 0
	v_pk_fma_f32 v[208:209], v[204:205], v[60:61], v[12:13] op_sel_hi:[0,1,1]
	v_pk_fma_f32 v[210:211], v[204:205], v[62:63], v[14:15] op_sel_hi:[0,1,1]
	v_pk_fma_f32 v[212:213], v[204:205], v[56:57], v[4:5] op_sel_hi:[0,1,1]
	v_pk_fma_f32 v[214:215], v[204:205], v[58:59], v[6:7] op_sel_hi:[0,1,1]
	v_pk_fma_f32 v[216:217], v[204:205], v[52:53], v[8:9] op_sel_hi:[0,1,1]
	v_pk_fma_f32 v[218:219], v[204:205], v[54:55], v[10:11] op_sel_hi:[0,1,1]
	v_pk_fma_f32 v[220:221], v[204:205], v[48:49], v[0:1] op_sel_hi:[0,1,1]
	v_pk_fma_f32 v[222:223], v[204:205], v[50:51], v[2:3] op_sel_hi:[0,1,1]
	v_pk_mul_f32 v[224:225], v[208:209], v[178:179] op_sel_hi:[1,0]
	v_pk_mul_f32 v[226:227], v[210:211], v[178:179] op_sel_hi:[1,0]
	v_pk_mul_f32 v[228:229], v[212:213], v[178:179] op_sel_hi:[1,0]
	v_pk_mul_f32 v[230:231], v[214:215], v[178:179] op_sel_hi:[1,0]
	v_exp_f32_e32 v224, v224
	v_exp_f32_e32 v225, v225
	v_exp_f32_e32 v226, v226
	v_exp_f32_e32 v227, v227
	v_exp_f32_e32 v228, v228
	v_exp_f32_e32 v229, v229
	v_exp_f32_e32 v230, v230
	v_exp_f32_e32 v231, v231
	v_pk_add_f32 v[224:225], v[224:225], 1.0 op_sel_hi:[1,0]
	v_pk_add_f32 v[226:227], v[226:227], 1.0 op_sel_hi:[1,0]
	v_pk_add_f32 v[228:229], v[228:229], 1.0 op_sel_hi:[1,0]
	v_pk_add_f32 v[230:231], v[230:231], 1.0 op_sel_hi:[1,0]
	v_rcp_f32_e32 v224, v224
	v_rcp_f32_e32 v225, v225
	v_rcp_f32_e32 v226, v226
	v_rcp_f32_e32 v227, v227
	v_rcp_f32_e32 v228, v228
	v_rcp_f32_e32 v229, v229
	v_rcp_f32_e32 v230, v230
	v_rcp_f32_e32 v231, v231
	v_pk_mul_f32 v[208:209], v[208:209], v[224:225]
	v_pk_mul_f32 v[210:211], v[210:211], v[226:227]
	v_pk_mul_f32 v[212:213], v[212:213], v[228:229]
	v_pk_mul_f32 v[214:215], v[214:215], v[230:231]
	v_pk_mul_f32 v[208:209], v[208:209], v[216:217]
	v_pk_mul_f32 v[210:211], v[210:211], v[218:219]
	v_pk_mul_f32 v[212:213], v[212:213], v[220:221]
	v_pk_mul_f32 v[214:215], v[214:215], v[222:223]
	v_cvt_pk_bf16_f32 v248, v208, v209
	v_cvt_pk_bf16_f32 v249, v210, v211
	v_cvt_pk_bf16_f32 v250, v212, v213
	v_cvt_pk_bf16_f32 v251, v214, v215
	global_store_dwordx4 v[232:233], v[248:251], off
	v_lshl_add_u64 v[232:233], v[232:233], 0, s[62:63]
	v_fmamk_f32 v176, v168, 0x3a800000, v166
	v_rsq_f32_e32 v176, v176
	s_nop 0
	v_pk_fma_f32 v[180:181], v[176:177], v[44:45], v[12:13] op_sel_hi:[0,1,1]
	v_pk_fma_f32 v[182:183], v[176:177], v[46:47], v[14:15] op_sel_hi:[0,1,1]
	v_pk_fma_f32 v[184:185], v[176:177], v[40:41], v[4:5] op_sel_hi:[0,1,1]
	v_pk_fma_f32 v[186:187], v[176:177], v[42:43], v[6:7] op_sel_hi:[0,1,1]
	v_pk_fma_f32 v[188:189], v[176:177], v[36:37], v[8:9] op_sel_hi:[0,1,1]
	v_pk_fma_f32 v[190:191], v[176:177], v[38:39], v[10:11] op_sel_hi:[0,1,1]
	v_pk_fma_f32 v[192:193], v[176:177], v[32:33], v[0:1] op_sel_hi:[0,1,1]
	v_pk_fma_f32 v[194:195], v[176:177], v[34:35], v[2:3] op_sel_hi:[0,1,1]
	v_pk_mul_f32 v[196:197], v[180:181], v[178:179] op_sel_hi:[1,0]
	v_pk_mul_f32 v[198:199], v[182:183], v[178:179] op_sel_hi:[1,0]
	v_pk_mul_f32 v[200:201], v[184:185], v[178:179] op_sel_hi:[1,0]
	v_pk_mul_f32 v[202:203], v[186:187], v[178:179] op_sel_hi:[1,0]
	v_exp_f32_e32 v196, v196
	v_exp_f32_e32 v197, v197
	v_exp_f32_e32 v198, v198
	v_exp_f32_e32 v199, v199
	v_exp_f32_e32 v200, v200
	v_exp_f32_e32 v201, v201
	v_exp_f32_e32 v202, v202
	v_exp_f32_e32 v203, v203
	v_pk_add_f32 v[196:197], v[196:197], 1.0 op_sel_hi:[1,0]
	v_pk_add_f32 v[198:199], v[198:199], 1.0 op_sel_hi:[1,0]
	v_pk_add_f32 v[200:201], v[200:201], 1.0 op_sel_hi:[1,0]
	v_pk_add_f32 v[202:203], v[202:203], 1.0 op_sel_hi:[1,0]
	v_rcp_f32_e32 v196, v196
	v_rcp_f32_e32 v197, v197
	v_rcp_f32_e32 v198, v198
	v_rcp_f32_e32 v199, v199
	v_rcp_f32_e32 v200, v200
	v_rcp_f32_e32 v201, v201
	v_rcp_f32_e32 v202, v202
	v_rcp_f32_e32 v203, v203
	v_pk_mul_f32 v[180:181], v[180:181], v[196:197]
	v_pk_mul_f32 v[182:183], v[182:183], v[198:199]
	v_pk_mul_f32 v[184:185], v[184:185], v[200:201]
	v_pk_mul_f32 v[186:187], v[186:187], v[202:203]
	v_pk_mul_f32 v[180:181], v[180:181], v[188:189]
	v_pk_mul_f32 v[182:183], v[182:183], v[190:191]
	v_pk_mul_f32 v[184:185], v[184:185], v[192:193]
	v_pk_mul_f32 v[186:187], v[186:187], v[194:195]
	v_cvt_pk_bf16_f32 v244, v180, v181
	v_cvt_pk_bf16_f32 v245, v182, v183
	v_cvt_pk_bf16_f32 v246, v184, v185
	v_cvt_pk_bf16_f32 v247, v186, v187
	global_store_dwordx4 v[232:233], v[244:247], off
	v_lshl_add_u64 v[232:233], v[232:233], 0, s[62:63]
	v_fmamk_f32 v204, v167, 0x3a800000, v166
	v_rsq_f32_e32 v204, v204
	s_nop 0
	v_pk_fma_f32 v[208:209], v[204:205], v[28:29], v[12:13] op_sel_hi:[0,1,1]
	v_pk_fma_f32 v[210:211], v[204:205], v[30:31], v[14:15] op_sel_hi:[0,1,1]
	v_pk_fma_f32 v[212:213], v[204:205], v[24:25], v[4:5] op_sel_hi:[0,1,1]
	v_pk_fma_f32 v[214:215], v[204:205], v[26:27], v[6:7] op_sel_hi:[0,1,1]
	v_pk_fma_f32 v[216:217], v[204:205], v[20:21], v[8:9] op_sel_hi:[0,1,1]
	v_pk_fma_f32 v[218:219], v[204:205], v[22:23], v[10:11] op_sel_hi:[0,1,1]
	v_pk_fma_f32 v[220:221], v[204:205], v[16:17], v[0:1] op_sel_hi:[0,1,1]
	v_pk_fma_f32 v[222:223], v[204:205], v[18:19], v[2:3] op_sel_hi:[0,1,1]
	v_pk_mul_f32 v[224:225], v[208:209], v[178:179] op_sel_hi:[1,0]
	v_pk_mul_f32 v[226:227], v[210:211], v[178:179] op_sel_hi:[1,0]
	v_pk_mul_f32 v[228:229], v[212:213], v[178:179] op_sel_hi:[1,0]
	v_pk_mul_f32 v[230:231], v[214:215], v[178:179] op_sel_hi:[1,0]
	v_exp_f32_e32 v224, v224
	v_exp_f32_e32 v225, v225
	v_exp_f32_e32 v226, v226
	v_exp_f32_e32 v227, v227
	v_exp_f32_e32 v228, v228
	v_exp_f32_e32 v229, v229
	v_exp_f32_e32 v230, v230
	v_exp_f32_e32 v231, v231
	v_pk_add_f32 v[224:225], v[224:225], 1.0 op_sel_hi:[1,0]
	v_pk_add_f32 v[226:227], v[226:227], 1.0 op_sel_hi:[1,0]
	v_pk_add_f32 v[228:229], v[228:229], 1.0 op_sel_hi:[1,0]
	v_pk_add_f32 v[230:231], v[230:231], 1.0 op_sel_hi:[1,0]
	v_rcp_f32_e32 v224, v224
	v_rcp_f32_e32 v225, v225
	v_rcp_f32_e32 v226, v226
	v_rcp_f32_e32 v227, v227
	v_rcp_f32_e32 v228, v228
	v_rcp_f32_e32 v229, v229
	v_rcp_f32_e32 v230, v230
	v_rcp_f32_e32 v231, v231
	v_pk_mul_f32 v[208:209], v[208:209], v[224:225]
	v_pk_mul_f32 v[210:211], v[210:211], v[226:227]
	v_pk_mul_f32 v[212:213], v[212:213], v[228:229]
	v_pk_mul_f32 v[214:215], v[214:215], v[230:231]
	v_pk_mul_f32 v[208:209], v[208:209], v[216:217]
	v_pk_mul_f32 v[210:211], v[210:211], v[218:219]
	v_pk_mul_f32 v[212:213], v[212:213], v[220:221]
	v_pk_mul_f32 v[214:215], v[214:215], v[222:223]
	v_cvt_pk_bf16_f32 v248, v208, v209
	v_cvt_pk_bf16_f32 v249, v210, v211
	v_cvt_pk_bf16_f32 v250, v212, v213
	v_cvt_pk_bf16_f32 v251, v214, v215
	global_store_dwordx4 v[232:233], v[248:251], off
	s_andn2_b64 vcc, exec, s[2:3]
	s_mov_b64 s[2:3], -1
	s_cbranch_vccnz .LBB0_940
; #define PG8_BAR __builtin_amdgcn_s_barrier()
;     __device__ __forceinline__ void prefetch(Pre& P, const Unit& u, int wr, int wc, int fr, int fq) const {
;         const float* bp = beta + (size_t)((u.pm * 256) >> 12) * (2 * FFH) + u.pn * 256 + wc * 32 + 8 * fq;
; #pragma unroll
;         for (int n = 0; n < 2; ++n) { P.bg[n] = *(const f32x4*)(bp + 4 * n); P.bu[n] = *(const f32x4*)(bp + 128 + 4 * n); }
; #pragma unroll
;         for (int ai = 0; ai < 2; ++ai)
; #pragma unroll
;             for (int m = 0; m < 4; ++m) P.r2[ai][m] = ssq2[u.pm * 256 + ai * 128 + wr * 64 + m * 16 + fr];
;     }
; template <class Epi, class Sched>
; __device__ __forceinline__ void gemm_phase(PG8_LAS unsigned char* lds, PG8_LAS unsigned char* ldx, const Gemm g, const Sched& S, const Epi& E, const int wid) {
;     ...
;         cur = nxt; cA = nA; cB = nB; ++ui;
;         E.prefetch(pre, cur, wr, wc, fr, fq);
;         if (wr == 1) PG8_BAR;
	s_ashr_i32 s2, s18, 4
	s_mul_hi_i32 s3, s2, 0x5800
	s_mulk_i32 s2, 0x5800
	s_add_u32 s17, s37, s2
	s_addc_u32 s19, s38, s3
	s_lshl_b32 s2, s16, 8
	s_ashr_i32 s3, s2, 31
	s_lshl_b64 s[2:3], s[2:3], 2
	s_add_u32 s2, s17, s2
	s_addc_u32 s3, s19, s3
	v_lshl_add_u32 v16, s18, 8, v162
	s_add_u32 s2, s2, s25
	v_ashrrev_i32_e32 v17, 31, v16
	s_addc_u32 s3, s3, 0
	v_lshl_add_u64 v[18:19], v[16:17], 2, s[8:9]
	v_add_u32_e32 v20, 0x80, v16
	v_add_u32_e32 v22, 0x90, v16
	v_add_u32_e32 v24, 0xa0, v16
	v_add_u32_e32 v16, 0xb0, v16
	v_lshl_add_u64 v[8:9], v[144:145], 2, s[2:3]
	v_ashrrev_i32_e32 v21, 31, v20
	v_ashrrev_i32_e32 v23, 31, v22
	v_ashrrev_i32_e32 v25, 31, v24
	v_ashrrev_i32_e32 v17, 31, v16
	global_load_dwordx4 v[4:7], v[8:9], off offset:16
	global_load_dwordx4 v[12:15], v[8:9], off
	global_load_dwordx4 v[0:3], v[8:9], off offset:528
	s_nop 0
	global_load_dwordx4 v[8:11], v[8:9], off offset:512
	v_lshl_add_u64 v[20:21], v[20:21], 2, s[8:9]
	v_lshl_add_u64 v[22:23], v[22:23], 2, s[8:9]
	v_lshl_add_u64 v[24:25], v[24:25], 2, s[8:9]
	v_lshl_add_u64 v[16:17], v[16:17], 2, s[8:9]
	global_load_dword v174, v[18:19], off
	global_load_dword v173, v[18:19], off offset:64
	global_load_dword v172, v[18:19], off offset:128
	global_load_dword v171, v[18:19], off offset:192
	global_load_dword v170, v[20:21], off
	global_load_dword v169, v[22:23], off
	global_load_dword v168, v[24:25], off
	global_load_dword v167, v[16:17], off
	s_andn2_b64 vcc, exec, s[6:7]
	s_cbranch_vccnz .LBB0_939
	s_barrier
	s_branch .LBB0_939
